# non-temporal hint on the prologue's streaming f32 source loads (weights read once), so the bf16 products stay cached for the first phases
# speedup vs baseline: 1.1004x; 1.0007x over previous
; #define LAS __attribute__((address_space(3)))
; #define TR_LOAD(it_) do { const int kb_ = (it_) / nblk, nb_ = (it_) % nblk; _Pragma("unroll") for (int i = 0; i < 8; ++i) r[i] = *(const f32x4*)(W + (size_t)(kb_ * 64 + 8 * i + (lane >> 3)) * ldw + nb_ * 32 + (lane & 7) * 4); } while (0)
; __device__ __forceinline__ void tr_job(const Ctx& c, int& rot, const float* W, int K, int N, int ldw, bf16_t* WT, int ldt, int row_off) {
;     LAS float* scr = (LAS float*)(c.lds + c.wave * 16384);
;     const int nblk = N / 32, items = (K / 64) * nblk;
;     int first = c.gw - (rot % c.ngw); if (first < 0) first += c.ngw;
;     int lane = c.lane; asm volatile("" : "+v"(lane));
;     f32x4 r[8];
;     ...
;     if (first < items) TR_LOAD(first);
; __device__ __forceinline__ void phase_prologue(KP P, const Ctx& c) {
;     ...
;         tr_job(c, rot, P->in[I_RGWIN] + (size_t)j * D * 4096, D, 4096, 4096, (bf16_t*)(ws + WS_RGIN) + (size_t)j * 4096 * D, D, 0);
.LBB0_35:
	s_mul_hi_u32 s10, s25, s22
	s_mul_i32 s10, s10, s21
	s_sub_i32 s10, s25, s10
	s_sub_i32 s11, s10, s21
	s_cmp_ge_u32 s10, s21
	s_cselect_b32 s10, s11, s10
	s_sub_i32 s11, s10, s21
	s_cmp_ge_u32 s10, s21
	s_cselect_b32 s10, s11, s10
	s_sub_i32 s10, s20, s10
	s_ashr_i32 s11, s10, 31
	s_and_b32 s11, s11, s14
	s_add_i32 s37, s11, s10
	v_mov_b32_e32 v38, v1
	s_cmpk_gt_i32 s37, 0xfff
	s_cbranch_scc1 .LBB0_40
	s_lshl_b64 s[10:11], s[8:9], 24
	s_add_u32 s10, s12, s10
	s_addc_u32 s11, s13, s11
	s_lshl_b64 s[40:41], s[8:9], 25
	s_waitcnt lgkmcnt(0)
	s_add_u32 s40, s4, s40
	s_addc_u32 s41, s5, s41
	s_ashr_i32 s43, s37, 31
	s_lshr_b32 s43, s43, 25
	s_add_i32 s43, s37, s43
	s_ashr_i32 s44, s43, 7
	s_and_b32 s43, s43, 0x7ffff80
	s_sub_i32 s43, s37, s43
	v_ashrrev_i32_e32 v40, 3, v38
	s_waitcnt vmcnt(11)
	v_lshl_add_u32 v2, s44, 6, v40
	s_lshl_b32 s44, s43, 5
	s_ashr_i32 s45, s44, 31
	s_lshl_b64 s[44:45], s[44:45], 2
	s_add_u32 s44, s40, s44
	v_lshlrev_b32_e32 v3, 4, v38
	s_addc_u32 s45, s41, s45
	v_and_b32_e32 v34, 0x70, v3
	v_ashrrev_i32_e32 v3, 31, v2
	v_lshl_add_u64 v[4:5], s[44:45], 0, v[34:35]
	v_lshlrev_b64 v[2:3], 14, v[2:3]
	s_waitcnt vmcnt(5)
	v_lshl_add_u64 v[26:27], v[4:5], 0, v[2:3]
	v_add_co_u32_e32 v10, vcc, s26, v26
	v_add_u32_e32 v41, s15, v34
	s_nop 0
	v_addc_co_u32_e32 v11, vcc, 0, v27, vcc
	global_load_dwordx4 v[2:5], v[26:27], off nt
	global_load_dwordx4 v[6:9], v[10:11], off nt
	v_add_co_u32_e32 v10, vcc, s27, v26
	v_lshl_add_u64 v[36:37], s[40:41], 0, v[34:35]
	s_nop 0
	v_addc_co_u32_e32 v11, vcc, 0, v27, vcc
	v_add_co_u32_e32 v14, vcc, s28, v26
	v_lshlrev_b32_e32 v34, 3, v38
	s_nop 0
	v_addc_co_u32_e32 v15, vcc, 0, v27, vcc
	v_add_co_u32_e32 v18, vcc, s29, v26
	global_load_dwordx4 v[10:13], v[10:11], off nt
	s_nop 0
	global_load_dwordx4 v[14:17], v[14:15], off nt
	v_addc_co_u32_e32 v19, vcc, 0, v27, vcc
	v_add_co_u32_e32 v22, vcc, s30, v26
	v_and_b32_e32 v34, 56, v34
	s_nop 0
	v_addc_co_u32_e32 v23, vcc, 0, v27, vcc
	v_add_co_u32_e32 v28, vcc, s31, v26
	global_load_dwordx4 v[18:21], v[18:19], off nt
	s_nop 0
	global_load_dwordx4 v[22:25], v[22:23], off nt
	v_addc_co_u32_e32 v29, vcc, 0, v27, vcc
	s_waitcnt vmcnt(10)
	v_add_co_u32_e32 v30, vcc, s34, v26
	v_mul_u32_u24_e32 v42, 0x84, v34
	s_nop 0
	v_addc_co_u32_e32 v31, vcc, 0, v27, vcc
	global_load_dwordx4 v[26:29], v[28:29], off nt
	s_nop 0
	global_load_dwordx4 v[30:33], v[30:31], off nt
	v_lshlrev_b32_e32 v34, 1, v34
	v_lshl_add_u64 v[38:39], s[10:11], 0, v[34:35]
	v_lshlrev_b32_e32 v34, 2, v40
	v_add3_u32 v34, s15, v42, v34
	v_mul_lo_u32 v42, v40, s35
	s_lshl_b32 s40, s37, 5
	v_add_u32_e32 v41, v41, v42
	s_mov_b32 s41, s36
	v_mov_b32_e32 v42, v40
	s_branch .LBB0_38

; #define LAS __attribute__((address_space(3)))
; #define TR_LOAD(it_) do { const int kb_ = (it_) / nblk, nb_ = (it_) % nblk; _Pragma("unroll") for (int i = 0; i < 8; ++i) r[i] = *(const f32x4*)(W + (size_t)(kb_ * 64 + 8 * i + (lane >> 3)) * ldw + nb_ * 32 + (lane & 7) * 4); } while (0)
; __device__ __forceinline__ void tr_job(const Ctx& c, int& rot, const float* W, int K, int N, int ldw, bf16_t* WT, int ldt, int row_off) {
;     LAS float* scr = (LAS float*)(c.lds + c.wave * 16384);
;     const int nblk = N / 32, items = (K / 64) * nblk;
;     int first = c.gw - (rot % c.ngw); if (first < 0) first += c.ngw;
;     int lane = c.lane; asm volatile("" : "+v"(lane));
;     f32x4 r[8];
;     ...
;     if (first < items) TR_LOAD(first);
;     for (int it = first; it < items; it += c.ngw) { const int kb = it / nblk, nb = it % nblk;
; #pragma unroll
;         for (int i = 0; i < 8; ++i) { LAS float* d = scr + (8 * i + (lane >> 3)) * 33 + (lane & 7) * 4; d[0] = r[i][0]; d[1] = r[i][1]; d[2] = r[i][2]; d[3] = r[i][3]; }
;         if (it + c.ngw < items) TR_LOAD(it + c.ngw);
; __device__ __forceinline__ void phase_prologue(KP P, const Ctx& c) {
;     ...
;         tr_job(c, rot, P->in[I_RGWIN] + (size_t)j * D * 4096, D, 4096, 4096, (bf16_t*)(ws + WS_RGIN) + (size_t)j * 4096 * D, D, 0);
;         tr_job(c, rot, P->in[I_RGWOUT] + (size_t)j * D * D, D, D, D, (bf16_t*)(ws + WS_RGOUT) + (size_t)j * D * D, D, 0);
.LBB0_38:
	v_add_u32_e32 v43, 0x420, v41
	s_waitcnt vmcnt(7)
	ds_write2_b32 v41, v2, v3 offset1:1
	ds_write2_b32 v41, v4, v5 offset0:2 offset1:3
	s_waitcnt vmcnt(6)
	ds_write2_b32 v43, v6, v7 offset1:1
	v_add_u32_e32 v43, 0x428, v41
	ds_write2_b32 v43, v8, v9 offset1:1
	v_add_u32_e32 v43, 0x840, v41
	s_waitcnt vmcnt(5)
	ds_write2_b32 v43, v10, v11 offset1:1
	v_add_u32_e32 v43, 0x848, v41
	ds_write2_b32 v43, v12, v13 offset1:1
	v_add_u32_e32 v43, 0xc60, v41
	s_waitcnt vmcnt(4)
	ds_write2_b32 v43, v14, v15 offset1:1
	v_add_u32_e32 v43, 0xc68, v41
	ds_write2_b32 v43, v16, v17 offset1:1
	v_add_u32_e32 v43, 0x1080, v41
	s_waitcnt vmcnt(3)
	ds_write2_b32 v43, v18, v19 offset1:1
	v_add_u32_e32 v43, 0x1088, v41
	ds_write2_b32 v43, v20, v21 offset1:1
	v_add_u32_e32 v43, 0x14a0, v41
	s_waitcnt vmcnt(2)
	ds_write2_b32 v43, v22, v23 offset1:1
	v_add_u32_e32 v43, 0x14a8, v41
	ds_write2_b32 v43, v24, v25 offset1:1
	v_add_u32_e32 v43, 0x18c0, v41
	s_add_i32 s43, s37, s14
	s_waitcnt vmcnt(1)
	ds_write2_b32 v43, v26, v27 offset1:1
	v_add_u32_e32 v43, 0x18c8, v41
	s_cmpk_gt_i32 s43, 0xfff
	ds_write2_b32 v43, v28, v29 offset1:1
	v_add_u32_e32 v43, 0x1ce0, v41
	s_cselect_b64 s[10:11], -1, 0
	s_waitcnt vmcnt(0)
	ds_write2_b32 v43, v30, v31 offset1:1
	v_add_u32_e32 v43, 0x1ce8, v41
	s_and_b64 vcc, exec, s[10:11]
	ds_write2_b32 v43, v32, v33 offset1:1
	s_cbranch_vccnz .LBB0_37
	s_ashr_i32 s44, s43, 31
	s_lshr_b32 s44, s44, 25
	s_add_i32 s44, s43, s44
	s_ashr_i32 s44, s44, 7
	v_lshl_add_u32 v2, s44, 6, v40
	s_add_i32 s45, s40, s41
	s_lshl_b32 s44, s44, 12
	s_sub_i32 s44, s45, s44
	s_ashr_i32 s45, s44, 31
	v_ashrrev_i32_e32 v3, 31, v2
	v_lshl_add_u64 v[4:5], s[44:45], 2, v[36:37]
	v_lshlrev_b64 v[2:3], 14, v[2:3]
	v_lshl_add_u64 v[26:27], v[4:5], 0, v[2:3]
	v_add_co_u32_e32 v6, vcc, s26, v26
	s_nop 1
	v_addc_co_u32_e32 v7, vcc, 0, v27, vcc
	v_add_co_u32_e32 v10, vcc, s27, v26
	global_load_dwordx4 v[2:5], v[26:27], off nt
	s_nop 0
	global_load_dwordx4 v[6:9], v[6:7], off nt
	v_addc_co_u32_e32 v11, vcc, 0, v27, vcc
	v_add_co_u32_e32 v14, vcc, s28, v26
	s_nop 1
	v_addc_co_u32_e32 v15, vcc, 0, v27, vcc
	v_add_co_u32_e32 v18, vcc, s29, v26
	global_load_dwordx4 v[10:13], v[10:11], off nt
	s_nop 0
	global_load_dwordx4 v[14:17], v[14:15], off nt
	v_addc_co_u32_e32 v19, vcc, 0, v27, vcc
	v_add_co_u32_e32 v22, vcc, s30, v26
	s_nop 1
	v_addc_co_u32_e32 v23, vcc, 0, v27, vcc
	v_add_co_u32_e32 v28, vcc, s31, v26
	global_load_dwordx4 v[18:21], v[18:19], off nt
	s_nop 0
	global_load_dwordx4 v[22:25], v[22:23], off nt
	v_addc_co_u32_e32 v29, vcc, 0, v27, vcc
	v_add_co_u32_e32 v30, vcc, s34, v26
	s_nop 1
	v_addc_co_u32_e32 v31, vcc, 0, v27, vcc
	global_load_dwordx4 v[26:29], v[28:29], off nt
	s_nop 0
	global_load_dwordx4 v[30:33], v[30:31], off nt
	s_branch .LBB0_37
.LBB0_40:
	s_add_i32 s10, s25, 0x1000
	s_mul_hi_u32 s11, s10, s22
	s_mul_i32 s11, s11, s21
	s_sub_i32 s10, s10, s11
	s_sub_i32 s11, s10, s21
	s_cmp_ge_u32 s10, s21
	s_cselect_b32 s10, s11, s10
	s_sub_i32 s11, s10, s21
	s_cmp_ge_u32 s10, s21
	s_cselect_b32 s10, s11, s10
	s_sub_i32 s10, s20, s10
	s_ashr_i32 s11, s10, 31
	s_and_b32 s11, s11, s14
	s_add_i32 s37, s11, s10
	v_mov_b32_e32 v38, v1
	s_cmpk_gt_i32 s37, 0x7ff
	s_cbranch_scc1 .LBB0_34
	s_load_dwordx2 s[40:41], s[18:19], 0x90
	s_lshl_b64 s[10:11], s[8:9], 23
	s_add_u32 s10, s23, s10
	s_addc_u32 s11, s24, s11
	s_lshl_b64 s[8:9], s[8:9], 24
	s_waitcnt lgkmcnt(0)
	s_add_u32 s8, s40, s8
	s_addc_u32 s9, s41, s9
	s_ashr_i32 s40, s37, 31
	s_lshr_b32 s40, s40, 26
	s_add_i32 s40, s37, s40
	s_andn2_b32 s40, s40, 63
	s_sub_i32 s41, s37, s40
	v_ashrrev_i32_e32 v40, 3, v38
	s_waitcnt vmcnt(5)
	v_add_u32_e32 v26, s40, v40
	s_lshl_b32 s40, s41, 5
	s_ashr_i32 s41, s40, 31
	s_lshl_b64 s[40:41], s[40:41], 2
	s_add_u32 s40, s8, s40
	v_lshlrev_b32_e32 v2, 4, v38
	v_add_u32_e32 v10, 16, v26
	s_addc_u32 s41, s9, s41
	v_and_b32_e32 v34, 0x70, v2
	v_ashrrev_i32_e32 v11, 31, v10
	v_lshl_add_u64 v[28:29], s[40:41], 0, v[34:35]
	v_add_u32_e32 v4, 8, v26
	v_lshlrev_b64 v[10:11], 13, v[10:11]
	v_ashrrev_i32_e32 v27, 31, v26
	v_ashrrev_i32_e32 v5, 31, v4
	v_lshl_add_u64 v[18:19], v[28:29], 0, v[10:11]
	v_add_u32_e32 v10, 24, v26
	v_lshlrev_b64 v[2:3], 13, v[26:27]
	v_lshlrev_b64 v[4:5], 13, v[4:5]
	v_ashrrev_i32_e32 v11, 31, v10
	v_lshl_add_u64 v[2:3], v[28:29], 0, v[2:3]
	v_lshl_add_u64 v[6:7], v[28:29], 0, v[4:5]
	v_lshlrev_b64 v[10:11], 13, v[10:11]
	global_load_dwordx4 v[2:5], v[2:3], off nt
	s_nop 0
	global_load_dwordx4 v[6:9], v[6:7], off nt
	v_lshl_add_u64 v[20:21], v[28:29], 0, v[10:11]
	global_load_dwordx4 v[10:13], v[18:19], off nt
	global_load_dwordx4 v[14:17], v[20:21], off nt
	v_add_u32_e32 v18, 32, v26
	v_ashrrev_i32_e32 v19, 31, v18
	v_lshlrev_b64 v[18:19], 13, v[18:19]
	s_waitcnt vmcnt(8)
	v_lshl_add_u64 v[30:31], v[28:29], 0, v[18:19]
	v_add_u32_e32 v18, 40, v26
	v_ashrrev_i32_e32 v19, 31, v18
	v_lshlrev_b64 v[18:19], 13, v[18:19]
	v_lshl_add_u64 v[32:33], v[28:29], 0, v[18:19]
	global_load_dwordx4 v[18:21], v[30:31], off nt
	global_load_dwordx4 v[22:25], v[32:33], off nt
	v_add_u32_e32 v30, 48, v26
	v_ashrrev_i32_e32 v31, 31, v30
	v_add_u32_e32 v26, 56, v26
	v_lshlrev_b64 v[30:31], 13, v[30:31]
	v_ashrrev_i32_e32 v27, 31, v26
	v_lshl_add_u64 v[36:37], v[28:29], 0, v[30:31]
	v_lshlrev_b64 v[26:27], 13, v[26:27]
	v_lshl_add_u64 v[42:43], v[28:29], 0, v[26:27]
	global_load_dwordx4 v[26:29], v[36:37], off nt
	global_load_dwordx4 v[30:33], v[42:43], off nt
	v_add_u32_e32 v41, s15, v34
	v_lshl_add_u64 v[36:37], s[8:9], 0, v[34:35]
	v_lshlrev_b32_e32 v34, 3, v38
	v_and_b32_e32 v34, 56, v34
	v_mul_u32_u24_e32 v42, 0x84, v34
	v_lshlrev_b32_e32 v34, 1, v34
	v_lshl_add_u64 v[38:39], s[10:11], 0, v[34:35]
	v_lshlrev_b32_e32 v34, 2, v40
	v_add3_u32 v34, s15, v42, v34
	v_mul_lo_u32 v42, v40, s35
	s_lshl_b32 s11, s14, 5
	s_lshl_b32 s10, s37, 5
	v_add_u32_e32 v41, v41, v42
	s_mov_b32 s40, s11
	v_mov_b32_e32 v42, v40
	s_branch .LBB0_43

; #define LAS __attribute__((address_space(3)))
; #define TR_LOAD(it_) do { const int kb_ = (it_) / nblk, nb_ = (it_) % nblk; _Pragma("unroll") for (int i = 0; i < 8; ++i) r[i] = *(const f32x4*)(W + (size_t)(kb_ * 64 + 8 * i + (lane >> 3)) * ldw + nb_ * 32 + (lane & 7) * 4); } while (0)
; __device__ __forceinline__ void tr_job(const Ctx& c, int& rot, const float* W, int K, int N, int ldw, bf16_t* WT, int ldt, int row_off) {
;     ...
;     if (first < items) TR_LOAD(first);
;     for (int it = first; it < items; it += c.ngw) { const int kb = it / nblk, nb = it % nblk;
; #pragma unroll
;         for (int i = 0; i < 8; ++i) { LAS float* d = scr + (8 * i + (lane >> 3)) * 33 + (lane & 7) * 4; d[0] = r[i][0]; d[1] = r[i][1]; d[2] = r[i][2]; d[3] = r[i][3]; }
;         if (it + c.ngw < items) TR_LOAD(it + c.ngw);
.LBB0_43:
	v_add_u32_e32 v43, 0x420, v41
	s_waitcnt vmcnt(7)
	ds_write2_b32 v41, v2, v3 offset1:1
	ds_write2_b32 v41, v4, v5 offset0:2 offset1:3
	s_waitcnt vmcnt(6)
	ds_write2_b32 v43, v6, v7 offset1:1
	v_add_u32_e32 v43, 0x428, v41
	ds_write2_b32 v43, v8, v9 offset1:1
	v_add_u32_e32 v43, 0x840, v41
	s_waitcnt vmcnt(5)
	ds_write2_b32 v43, v10, v11 offset1:1
	v_add_u32_e32 v43, 0x848, v41
	ds_write2_b32 v43, v12, v13 offset1:1
	v_add_u32_e32 v43, 0xc60, v41
	s_waitcnt vmcnt(4)
	ds_write2_b32 v43, v14, v15 offset1:1
	v_add_u32_e32 v43, 0xc68, v41
	ds_write2_b32 v43, v16, v17 offset1:1
	v_add_u32_e32 v43, 0x1080, v41
	s_waitcnt vmcnt(3)
	ds_write2_b32 v43, v18, v19 offset1:1
	v_add_u32_e32 v43, 0x1088, v41
	ds_write2_b32 v43, v20, v21 offset1:1
	v_add_u32_e32 v43, 0x14a0, v41
	s_waitcnt vmcnt(2)
	ds_write2_b32 v43, v22, v23 offset1:1
	v_add_u32_e32 v43, 0x14a8, v41
	ds_write2_b32 v43, v24, v25 offset1:1
	v_add_u32_e32 v43, 0x18c0, v41
	s_add_i32 s41, s37, s14
	s_waitcnt vmcnt(1)
	ds_write2_b32 v43, v26, v27 offset1:1
	v_add_u32_e32 v43, 0x18c8, v41
	s_cmpk_gt_i32 s41, 0x7ff
	ds_write2_b32 v43, v28, v29 offset1:1
	v_add_u32_e32 v43, 0x1ce0, v41
	s_cselect_b64 s[8:9], -1, 0
	s_waitcnt vmcnt(0)
	ds_write2_b32 v43, v30, v31 offset1:1
	v_add_u32_e32 v43, 0x1ce8, v41
	s_and_b64 vcc, exec, s[8:9]
	ds_write2_b32 v43, v32, v33 offset1:1
	s_cbranch_vccnz .LBB0_42
	s_ashr_i32 s43, s41, 31
	s_lshr_b32 s43, s43, 26
	s_add_i32 s43, s41, s43
	s_and_b32 s44, s43, 0xffffffc0
	s_lshl_b32 s43, s43, 5
	v_add_u32_e32 v26, s44, v40
	s_add_i32 s44, s10, s40
	s_and_b32 s43, s43, 0xfffff800
	s_sub_i32 s44, s44, s43
	s_ashr_i32 s45, s44, 31
	v_ashrrev_i32_e32 v27, 31, v26
	v_lshl_add_u64 v[28:29], s[44:45], 2, v[36:37]
	v_lshlrev_b64 v[2:3], 13, v[26:27]
	v_lshl_add_u64 v[10:11], v[28:29], 0, v[2:3]
	v_add_u32_e32 v2, 8, v26
	v_ashrrev_i32_e32 v3, 31, v2
	v_lshlrev_b64 v[2:3], 13, v[2:3]
	v_lshl_add_u64 v[12:13], v[28:29], 0, v[2:3]
	global_load_dwordx4 v[2:5], v[10:11], off nt
	global_load_dwordx4 v[6:9], v[12:13], off nt
	v_add_u32_e32 v10, 16, v26
	v_ashrrev_i32_e32 v11, 31, v10
	v_lshlrev_b64 v[10:11], 13, v[10:11]
	v_lshl_add_u64 v[18:19], v[28:29], 0, v[10:11]
	v_add_u32_e32 v10, 24, v26
	v_ashrrev_i32_e32 v11, 31, v10
	v_lshlrev_b64 v[10:11], 13, v[10:11]
	v_lshl_add_u64 v[20:21], v[28:29], 0, v[10:11]
	global_load_dwordx4 v[10:13], v[18:19], off nt
	global_load_dwordx4 v[14:17], v[20:21], off nt
	v_add_u32_e32 v18, 32, v26
	v_ashrrev_i32_e32 v19, 31, v18
	v_lshlrev_b64 v[18:19], 13, v[18:19]
	v_lshl_add_u64 v[30:31], v[28:29], 0, v[18:19]
	v_add_u32_e32 v18, 40, v26
	v_ashrrev_i32_e32 v19, 31, v18
	v_lshlrev_b64 v[18:19], 13, v[18:19]
	v_lshl_add_u64 v[32:33], v[28:29], 0, v[18:19]
	global_load_dwordx4 v[18:21], v[30:31], off nt
	global_load_dwordx4 v[22:25], v[32:33], off nt
	v_add_u32_e32 v30, 48, v26
	v_ashrrev_i32_e32 v31, 31, v30
	v_add_u32_e32 v26, 56, v26
	v_lshlrev_b64 v[30:31], 13, v[30:31]
	v_ashrrev_i32_e32 v27, 31, v26
	v_lshl_add_u64 v[44:45], v[28:29], 0, v[30:31]
	v_lshlrev_b64 v[26:27], 13, v[26:27]
	v_lshl_add_u64 v[46:47], v[28:29], 0, v[26:27]
	global_load_dwordx4 v[26:29], v[44:45], off nt
	global_load_dwordx4 v[30:33], v[46:47], off nt
	s_branch .LBB0_42

; #define LAS __attribute__((address_space(3)))
; #define LDS_WAIT() asm volatile("s_waitcnt lgkmcnt(0)" ::: "memory")
; __device__ __forceinline__ void transpose_item(const float* W, int ldw, bf16_t* WT, int ldt, int k0, int n0, int dst_row0, LAS float* scr, int lane) {
; #pragma unroll
;     for (int i = 0; i < 8; ++i) { const int kk = 8 * i + (lane >> 3), nn = (lane & 7) * 4; const f32x4 wv = *(const f32x4*)(W + (size_t)(k0 + kk) * ldw + n0 + nn);
;         LAS float* d = scr + kk * 33 + nn; d[0] = wv[0]; d[1] = wv[1]; d[2] = wv[2]; d[3] = wv[3]; }
;     LDS_WAIT(); asm volatile("" ::: "memory");
;     const int c = lane & 7;
; #pragma unroll
;     for (int j = 0; j < 4; ++j) { const int n = (lane >> 3) + 8 * j; const LAS float* s = scr + (8 * c) * 33 + n;
;         u32x4 o; o.x = cvt_pk_bf16(s[0 * 33], s[1 * 33]); o.y = cvt_pk_bf16(s[2 * 33], s[3 * 33]); o.z = cvt_pk_bf16(s[4 * 33], s[5 * 33]); o.w = cvt_pk_bf16(s[6 * 33], s[7 * 33]);
;         *(u32x4*)(WT + (size_t)(dst_row0 + n) * ldt + k0 + 8 * c) = o; }
;     LDS_WAIT(); asm volatile("" ::: "memory");
; }
; __device__ __forceinline__ void phase_prologue(KP P, const Ctx& c) {
;     ...
;         for (int it = first; it < items; it += c.ngw) {
;             const int mat = it >> 5, sub = it & 31, kb = sub >> 3, nb32 = sub & 7;
;             const int jl = mat >> 5, d = (mat >> 4) & 1, g = (mat >> 3) & 1, nblk = mat & 7;
;             const int n0 = nb32 * 32, hf = n0 >> 7, pn = (d * 8 + nblk) * 2 + hf;
;             transpose_item(P->in[I_RGGW] + (size_t)mat * 65536, 256, (bf16_t*)(ws + WS_RGGATE) + (size_t)jl * 8192 * 256, 256, kb * 64, n0, pn * 256 + g * 128 + (n0 & 127), scr, c.lane);
;         }
.LBB0_47:
	s_ashr_i32 s24, s6, 5
	s_lshr_b32 s23, s6, 6
	s_and_b32 s27, s24, 7
	s_and_b32 s23, s23, 8
	s_ashr_i32 s25, s24, 31
	s_ashr_i32 s26, s6, 10
	s_and_b32 s13, s11, 0xe0
	s_or_b32 s23, s23, s27
	s_lshl_b64 s[24:25], s[24:25], 18
	s_waitcnt lgkmcnt(0)
	s_add_u32 s28, s4, s24
	s_addc_u32 s29, s5, s25
	s_ashr_i32 s27, s26, 31
	s_lshl_b64 s[24:25], s[26:27], 22
	s_add_u32 s26, s7, s24
	s_addc_u32 s27, s8, s25
	s_lshl_b32 s24, s11, 1
	s_lshl_b32 s23, s23, 9
	s_lshr_b32 s25, s6, 1
	s_and_b32 s24, s24, 0x100
	s_and_b32 s25, s25, 0x80
	s_or_b32 s23, s23, s24
	s_and_b32 s31, s11, 0x60
	s_or_b32 s23, s23, s25
	s_and_b32 s30, s9, 0xc0
	s_lshl_b32 s13, s13, 2
	s_or_b32 s23, s23, s31
	s_add_u32 s24, s28, s13
	v_or_b32_e32 v2, s30, v8
	s_addc_u32 s25, s29, 0
	v_or_b32_e32 v32, s30, v9
	v_lshlrev_b32_e32 v2, 10, v2
	v_lshl_add_u64 v[60:61], s[24:25], 0, v[4:5]
	v_or_b32_e32 v33, s30, v10
	v_lshl_add_u64 v[40:41], v[60:61], 0, v[2:3]
	v_lshlrev_b32_e32 v2, 10, v32
	v_or_b32_e32 v44, s30, v11
	v_lshl_add_u64 v[42:43], v[60:61], 0, v[2:3]
	v_lshlrev_b32_e32 v2, 10, v33
	v_or_b32_e32 v45, s30, v12
	v_lshl_add_u64 v[48:49], v[60:61], 0, v[2:3]
	v_lshlrev_b32_e32 v2, 10, v44
	v_or_b32_e32 v52, s30, v13
	v_lshl_add_u64 v[50:51], v[60:61], 0, v[2:3]
	v_lshlrev_b32_e32 v2, 10, v45
	v_or_b32_e32 v53, s30, v14
	v_lshl_add_u64 v[56:57], v[60:61], 0, v[2:3]
	v_lshlrev_b32_e32 v2, 10, v52
	global_load_dwordx4 v[32:35], v[40:41], off nt
	global_load_dwordx4 v[36:39], v[42:43], off nt
	s_nop 0
	global_load_dwordx4 v[40:43], v[48:49], off nt
	global_load_dwordx4 v[44:47], v[50:51], off nt
	v_lshl_add_u64 v[58:59], v[60:61], 0, v[2:3]
	v_lshlrev_b32_e32 v2, 10, v53
	global_load_dwordx4 v[48:51], v[56:57], off nt
	global_load_dwordx4 v[52:55], v[58:59], off nt
	v_or_b32_e32 v62, s30, v15
	v_lshl_add_u64 v[56:57], v[60:61], 0, v[2:3]
	v_lshlrev_b32_e32 v2, 10, v62
	global_load_dwordx4 v[56:59], v[56:57], off nt
	v_lshl_add_u64 v[60:61], v[60:61], 0, v[2:3]
	global_load_dwordx4 v[60:63], v[60:61], off nt
	v_or_b32_e32 v2, s23, v8
	s_lshl_b32 s13, s30, 1
	v_lshlrev_b64 v[66:67], 9, v[2:3]
	v_or_b32_e32 v2, s23, v9
	s_add_u32 s24, s26, s13
	v_lshlrev_b64 v[68:69], 9, v[2:3]
	v_or_b32_e32 v2, s23, v10
	s_addc_u32 s25, s27, 0
	v_lshlrev_b64 v[70:71], 9, v[2:3]
	v_or_b32_e32 v2, s23, v11
	v_lshl_add_u64 v[64:65], s[24:25], 0, v[6:7]
	v_lshlrev_b64 v[72:73], 9, v[2:3]
	v_lshl_add_u64 v[66:67], v[64:65], 0, v[66:67]
	v_lshl_add_u64 v[68:69], v[64:65], 0, v[68:69]
	v_lshl_add_u64 v[70:71], v[64:65], 0, v[70:71]
	v_lshl_add_u64 v[64:65], v[64:65], 0, v[72:73]
	s_add_i32 s6, s6, s14
	s_add_i32 s9, s9, s10
	s_add_i32 s11, s11, s12
	s_cmpk_gt_i32 s6, 0x7ff
	s_waitcnt vmcnt(7)
	ds_write2_b32 v17, v32, v33 offset1:1
	ds_write2_b32 v17, v34, v35 offset0:2 offset1:3
	s_waitcnt vmcnt(6)
	ds_write2_b32 v18, v36, v37 offset1:1
	ds_write2_b32 v19, v38, v39 offset1:1
	s_waitcnt vmcnt(5)
	ds_write2_b32 v20, v40, v41 offset1:1
	ds_write2_b32 v21, v42, v43 offset1:1
	s_waitcnt vmcnt(4)
	ds_write2_b32 v22, v44, v45 offset1:1
	ds_write2_b32 v23, v46, v47 offset1:1
	s_waitcnt vmcnt(3)
	ds_write2_b32 v24, v48, v49 offset1:1
	ds_write2_b32 v25, v50, v51 offset1:1
	s_waitcnt vmcnt(2)
	ds_write2_b32 v26, v52, v53 offset1:1
	ds_write2_b32 v27, v54, v55 offset1:1
	s_waitcnt vmcnt(1)
	ds_write2_b32 v28, v56, v57 offset1:1
	ds_write2_b32 v29, v58, v59 offset1:1
	s_waitcnt vmcnt(0)
	ds_write2_b32 v30, v60, v61 offset1:1
	ds_write2_b32 v31, v62, v63 offset1:1
	s_waitcnt lgkmcnt(0)
	ds_read2_b32 v[36:37], v16 offset0:33 offset1:41
	ds_read2_b32 v[38:39], v16 offset1:8
	ds_read2_b32 v[40:41], v16 offset0:66 offset1:74
	ds_read2_b32 v[42:43], v16 offset0:99 offset1:107
	ds_read2_b32 v[44:45], v16 offset0:132 offset1:140
	ds_read2_b32 v[46:47], v16 offset0:165 offset1:173
	ds_read2_b32 v[48:49], v16 offset0:198 offset1:206
	ds_read2_b32 v[50:51], v16 offset0:231 offset1:239
	ds_read2_b32 v[52:53], v16 offset0:49 offset1:57
	ds_read2_b32 v[54:55], v16 offset0:16 offset1:24
	ds_read2_b32 v[56:57], v16 offset0:82 offset1:90
	ds_read2_b32 v[58:59], v16 offset0:115 offset1:123
	ds_read2_b32 v[60:61], v16 offset0:148 offset1:156
	ds_read2_b32 v[62:63], v16 offset0:181 offset1:189
	ds_read2_b32 v[72:73], v16 offset0:214 offset1:222
	ds_read2_b32 v[74:75], v16 offset0:247 offset1:255
	s_waitcnt lgkmcnt(14)
	v_cvt_pk_bf16_f32 v32, v38, v36
	s_waitcnt lgkmcnt(12)
	v_cvt_pk_bf16_f32 v33, v40, v42
	s_waitcnt lgkmcnt(10)
	v_cvt_pk_bf16_f32 v34, v44, v46
	s_waitcnt lgkmcnt(8)
	v_cvt_pk_bf16_f32 v35, v48, v50
	v_cvt_pk_bf16_f32 v36, v39, v37
	v_cvt_pk_bf16_f32 v37, v41, v43
	v_cvt_pk_bf16_f32 v38, v45, v47
	v_cvt_pk_bf16_f32 v39, v49, v51
	s_waitcnt lgkmcnt(6)
	v_cvt_pk_bf16_f32 v40, v54, v52
	s_waitcnt lgkmcnt(4)
	v_cvt_pk_bf16_f32 v41, v56, v58
	s_waitcnt lgkmcnt(2)
	v_cvt_pk_bf16_f32 v42, v60, v62
	s_waitcnt lgkmcnt(0)
	v_cvt_pk_bf16_f32 v43, v72, v74
	v_cvt_pk_bf16_f32 v44, v55, v53
	v_cvt_pk_bf16_f32 v45, v57, v59
	v_cvt_pk_bf16_f32 v46, v61, v63
	v_cvt_pk_bf16_f32 v47, v73, v75
	global_store_dwordx4 v[66:67], v[32:35], off
	global_store_dwordx4 v[68:69], v[36:39], off
	global_store_dwordx4 v[70:71], v[40:43], off
	global_store_dwordx4 v[64:65], v[44:47], off
	s_waitcnt lgkmcnt(0)
	s_cbranch_scc0 .LBB0_47
; #define LAS __attribute__((address_space(3)))
; #define TR_LOAD(it_) do { const int kb_ = (it_) / nblk, nb_ = (it_) % nblk; _Pragma("unroll") for (int i = 0; i < 8; ++i) r[i] = *(const f32x4*)(W + (size_t)(kb_ * 64 + 8 * i + (lane >> 3)) * ldw + nb_ * 32 + (lane & 7) * 4); } while (0)
; __device__ __forceinline__ void tr_job(const Ctx& c, int& rot, const float* W, int K, int N, int ldw, bf16_t* WT, int ldt, int row_off) {
;     LAS float* scr = (LAS float*)(c.lds + c.wave * 16384);
;     const int nblk = N / 32, items = (K / 64) * nblk;
;     int first = c.gw - (rot % c.ngw); if (first < 0) first += c.ngw;
;     int lane = c.lane; asm volatile("" : "+v"(lane));
;     f32x4 r[8];
;     ...
;     if (first < items) TR_LOAD(first);
; __device__ __forceinline__ void phase_prologue(KP P, const Ctx& c) {
;     ...
;     for (int m = 0; m < 3; ++m) tr_job(c, rot, P->in[I_RWRKV] + (size_t)m * D * D, D, D, D, (bf16_t*)(ws + WS_RW1), D, m * D);
.LBB0_48:
	s_mul_hi_u32 s6, s22, 0x3800
	s_add_u32 s8, s16, 0x7c00000
	s_mul_i32 s6, s6, s21
	s_addc_u32 s9, s17, 0
	s_sub_i32 s6, 0x3800, s6
	s_sub_i32 s7, s6, s21
	s_cmp_ge_u32 s6, s21
	s_cselect_b32 s6, s7, s6
	s_sub_i32 s7, s6, s21
	s_cmp_ge_u32 s6, s21
	s_cselect_b32 s6, s7, s6
	s_load_dwordx2 s[4:5], s[18:19], 0xa0
	s_sub_i32 s6, s20, s6
	s_ashr_i32 s7, s6, 31
	s_and_b32 s7, s7, s14
	s_add_i32 s10, s7, s6
	v_mov_b32_e32 v36, v1
	s_cmpk_lt_i32 s10, 0x800
	s_cbranch_scc0 .LBB0_53
	s_cmpk_eq_i32 s3, 0x100
	s_cbranch_scc1 .LBB0_53
	s_ashr_i32 s6, s10, 31
	s_lshr_b32 s6, s6, 26
	s_add_i32 s6, s10, s6
	s_andn2_b32 s6, s6, 63
	s_sub_i32 s7, s10, s6
	v_ashrrev_i32_e32 v38, 3, v36
	s_waitcnt vmcnt(5)
	v_add_u32_e32 v26, s6, v38
	s_lshl_b32 s6, s7, 5
	s_ashr_i32 s7, s6, 31
	s_lshl_b64 s[6:7], s[6:7], 2
	s_waitcnt lgkmcnt(0)
	s_add_u32 s6, s4, s6
	v_lshlrev_b32_e32 v2, 4, v36
	s_addc_u32 s7, s5, s7
	v_and_b32_e32 v40, 0x70, v2
	v_mov_b32_e32 v41, 0
	v_ashrrev_i32_e32 v27, 31, v26
	v_lshl_add_u64 v[28:29], s[6:7], 0, v[40:41]
	v_lshlrev_b64 v[2:3], 13, v[26:27]
	v_lshl_add_u64 v[10:11], v[28:29], 0, v[2:3]
	v_add_u32_e32 v2, 8, v26
	v_ashrrev_i32_e32 v3, 31, v2
	v_lshlrev_b64 v[2:3], 13, v[2:3]
	v_lshl_add_u64 v[12:13], v[28:29], 0, v[2:3]
	global_load_dwordx4 v[2:5], v[10:11], off nt
	global_load_dwordx4 v[6:9], v[12:13], off nt
	v_add_u32_e32 v10, 16, v26
	v_ashrrev_i32_e32 v11, 31, v10
	v_lshlrev_b64 v[10:11], 13, v[10:11]
	v_lshl_add_u64 v[18:19], v[28:29], 0, v[10:11]
	v_add_u32_e32 v10, 24, v26
	v_ashrrev_i32_e32 v11, 31, v10
	v_lshlrev_b64 v[10:11], 13, v[10:11]
	v_lshl_add_u64 v[20:21], v[28:29], 0, v[10:11]
	global_load_dwordx4 v[10:13], v[18:19], off nt
	global_load_dwordx4 v[14:17], v[20:21], off nt
	v_add_u32_e32 v18, 32, v26
	v_ashrrev_i32_e32 v19, 31, v18
	v_lshlrev_b64 v[18:19], 13, v[18:19]
	s_waitcnt vmcnt(8)
	v_lshl_add_u64 v[30:31], v[28:29], 0, v[18:19]
	v_add_u32_e32 v18, 40, v26
	v_ashrrev_i32_e32 v19, 31, v18
	v_lshlrev_b64 v[18:19], 13, v[18:19]
	v_lshl_add_u64 v[32:33], v[28:29], 0, v[18:19]
	global_load_dwordx4 v[18:21], v[30:31], off nt
	global_load_dwordx4 v[22:25], v[32:33], off nt
	v_add_u32_e32 v30, 48, v26
	v_ashrrev_i32_e32 v31, 31, v30
	v_add_u32_e32 v26, 56, v26
	v_lshlrev_b64 v[30:31], 13, v[30:31]
	v_ashrrev_i32_e32 v27, 31, v26
	v_lshl_add_u64 v[34:35], v[28:29], 0, v[30:31]
	v_lshlrev_b64 v[26:27], 13, v[26:27]
	v_lshl_add_u64 v[42:43], v[28:29], 0, v[26:27]
	global_load_dwordx4 v[26:29], v[34:35], off nt
	global_load_dwordx4 v[30:33], v[42:43], off nt
	v_lshlrev_b32_e32 v36, 3, v36
	v_and_b32_e32 v36, 56, v36
	v_add_u32_e32 v42, s15, v40
	v_lshl_add_u64 v[34:35], s[4:5], 0, v[40:41]
	v_lshlrev_b32_e32 v40, 1, v36
	s_movk_i32 s6, 0x84
	v_mul_u32_u24_e32 v39, 0x84, v36
	v_lshl_add_u64 v[36:37], s[8:9], 0, v[40:41]
	v_lshlrev_b32_e32 v40, 2, v38
	v_add3_u32 v39, s15, v39, v40
	v_mul_lo_u32 v40, v38, s6
	s_lshl_b32 s12, s14, 5
	s_lshl_b32 s11, s10, 5
	v_add_u32_e32 v40, v42, v40
	s_mov_b32 s13, s12
	v_mov_b32_e32 v41, v38
	s_branch .LBB0_51

; #define LAS __attribute__((address_space(3)))
; #define TR_LOAD(it_) do { const int kb_ = (it_) / nblk, nb_ = (it_) % nblk; _Pragma("unroll") for (int i = 0; i < 8; ++i) r[i] = *(const f32x4*)(W + (size_t)(kb_ * 64 + 8 * i + (lane >> 3)) * ldw + nb_ * 32 + (lane & 7) * 4); } while (0)
; __device__ __forceinline__ void tr_job(const Ctx& c, int& rot, const float* W, int K, int N, int ldw, bf16_t* WT, int ldt, int row_off) {
;     LAS float* scr = (LAS float*)(c.lds + c.wave * 16384);
;     const int nblk = N / 32, items = (K / 64) * nblk;
;     int first = c.gw - (rot % c.ngw); if (first < 0) first += c.ngw;
;     int lane = c.lane; asm volatile("" : "+v"(lane));
;     f32x4 r[8];
;     ...
;     if (first < items) TR_LOAD(first);
;     for (int it = first; it < items; it += c.ngw) { const int kb = it / nblk, nb = it % nblk;
; #pragma unroll
;         for (int i = 0; i < 8; ++i) { LAS float* d = scr + (8 * i + (lane >> 3)) * 33 + (lane & 7) * 4; d[0] = r[i][0]; d[1] = r[i][1]; d[2] = r[i][2]; d[3] = r[i][3]; }
;         if (it + c.ngw < items) TR_LOAD(it + c.ngw);
; __device__ __forceinline__ void phase_prologue(KP P, const Ctx& c) {
;     ...
;     for (int m = 0; m < 3; ++m) tr_job(c, rot, P->in[I_RWRKV] + (size_t)m * D * D, D, D, D, (bf16_t*)(ws + WS_RW1), D, m * D);
.LBB0_51:
	v_add_u32_e32 v42, 0x420, v40
	s_waitcnt vmcnt(7)
	ds_write2_b32 v40, v2, v3 offset1:1
	ds_write2_b32 v40, v4, v5 offset0:2 offset1:3
	s_waitcnt vmcnt(6)
	ds_write2_b32 v42, v6, v7 offset1:1
	v_add_u32_e32 v42, 0x428, v40
	ds_write2_b32 v42, v8, v9 offset1:1
	v_add_u32_e32 v42, 0x840, v40
	s_waitcnt vmcnt(5)
	ds_write2_b32 v42, v10, v11 offset1:1
	v_add_u32_e32 v42, 0x848, v40
	ds_write2_b32 v42, v12, v13 offset1:1
	v_add_u32_e32 v42, 0xc60, v40
	s_waitcnt vmcnt(4)
	ds_write2_b32 v42, v14, v15 offset1:1
	v_add_u32_e32 v42, 0xc68, v40
	ds_write2_b32 v42, v16, v17 offset1:1
	v_add_u32_e32 v42, 0x1080, v40
	s_waitcnt vmcnt(3)
	ds_write2_b32 v42, v18, v19 offset1:1
	v_add_u32_e32 v42, 0x1088, v40
	ds_write2_b32 v42, v20, v21 offset1:1
	v_add_u32_e32 v42, 0x14a0, v40
	s_waitcnt vmcnt(2)
	ds_write2_b32 v42, v22, v23 offset1:1
	v_add_u32_e32 v42, 0x14a8, v40
	ds_write2_b32 v42, v24, v25 offset1:1
	v_add_u32_e32 v42, 0x18c0, v40
	s_add_i32 s23, s10, s14
	s_waitcnt vmcnt(1)
	ds_write2_b32 v42, v26, v27 offset1:1
	v_add_u32_e32 v42, 0x18c8, v40
	s_cmpk_gt_i32 s23, 0x7ff
	ds_write2_b32 v42, v28, v29 offset1:1
	v_add_u32_e32 v42, 0x1ce0, v40
	s_cselect_b64 s[6:7], -1, 0
	s_waitcnt vmcnt(0)
	ds_write2_b32 v42, v30, v31 offset1:1
	v_add_u32_e32 v42, 0x1ce8, v40
	s_and_b64 vcc, exec, s[6:7]
	ds_write2_b32 v42, v32, v33 offset1:1
	s_cbranch_vccnz .LBB0_50
	s_ashr_i32 s24, s23, 31
	s_lshr_b32 s24, s24, 26
	s_add_i32 s24, s23, s24
	s_and_b32 s25, s24, 0xffffffc0
	s_lshl_b32 s24, s24, 5
	v_add_u32_e32 v26, s25, v38
	s_add_i32 s25, s11, s13
	s_and_b32 s24, s24, 0xfffff800
	s_sub_i32 s24, s25, s24
	s_ashr_i32 s25, s24, 31
	v_ashrrev_i32_e32 v27, 31, v26
	v_lshl_add_u64 v[28:29], s[24:25], 2, v[34:35]
	v_lshlrev_b64 v[2:3], 13, v[26:27]
	v_lshl_add_u64 v[10:11], v[28:29], 0, v[2:3]
	v_add_u32_e32 v2, 8, v26
	v_ashrrev_i32_e32 v3, 31, v2
	v_lshlrev_b64 v[2:3], 13, v[2:3]
	v_lshl_add_u64 v[12:13], v[28:29], 0, v[2:3]
	global_load_dwordx4 v[2:5], v[10:11], off nt
	global_load_dwordx4 v[6:9], v[12:13], off nt
	v_add_u32_e32 v10, 16, v26
	v_ashrrev_i32_e32 v11, 31, v10
	v_lshlrev_b64 v[10:11], 13, v[10:11]
	v_lshl_add_u64 v[18:19], v[28:29], 0, v[10:11]
	v_add_u32_e32 v10, 24, v26
	v_ashrrev_i32_e32 v11, 31, v10
	v_lshlrev_b64 v[10:11], 13, v[10:11]
	v_lshl_add_u64 v[20:21], v[28:29], 0, v[10:11]
	global_load_dwordx4 v[10:13], v[18:19], off nt
	global_load_dwordx4 v[14:17], v[20:21], off nt
	v_add_u32_e32 v18, 32, v26
	v_ashrrev_i32_e32 v19, 31, v18
	v_lshlrev_b64 v[18:19], 13, v[18:19]
	v_lshl_add_u64 v[30:31], v[28:29], 0, v[18:19]
	v_add_u32_e32 v18, 40, v26
	v_ashrrev_i32_e32 v19, 31, v18
	v_lshlrev_b64 v[18:19], 13, v[18:19]
	v_lshl_add_u64 v[32:33], v[28:29], 0, v[18:19]
	global_load_dwordx4 v[18:21], v[30:31], off nt
	global_load_dwordx4 v[22:25], v[32:33], off nt
	v_add_u32_e32 v30, 48, v26
	v_ashrrev_i32_e32 v31, 31, v30
	v_add_u32_e32 v26, 56, v26
	v_lshlrev_b64 v[30:31], 13, v[30:31]
	v_ashrrev_i32_e32 v27, 31, v26
	v_lshl_add_u64 v[42:43], v[28:29], 0, v[30:31]
	v_lshlrev_b64 v[26:27], 13, v[26:27]
	v_lshl_add_u64 v[44:45], v[28:29], 0, v[26:27]
	global_load_dwordx4 v[26:29], v[42:43], off nt
	global_load_dwordx4 v[30:33], v[44:45], off nt
	s_branch .LBB0_50
.LBB0_53:
	s_lshr_b32 s6, s22, 18
	s_mul_i32 s6, s6, s21
	s_sub_i32 s6, 0x4000, s6
	s_sub_i32 s7, s6, s21
	s_cmp_ge_u32 s6, s21
	s_cselect_b32 s6, s7, s6
	s_sub_i32 s7, s6, s21
	s_cmp_ge_u32 s6, s21
	s_cselect_b32 s6, s7, s6
	s_sub_i32 s6, s20, s6
	s_ashr_i32 s7, s6, 31
	s_and_b32 s7, s7, s14
	s_add_i32 s10, s7, s6
	v_mov_b32_e32 v36, v1
	s_cmpk_gt_i32 s10, 0x7ff
	s_cbranch_scc1 .LBB0_58
	s_cmpk_eq_i32 s3, 0x100
	s_cbranch_scc1 .LBB0_58
	s_waitcnt lgkmcnt(0)
	s_add_u32 s6, s4, 0x1000000
	s_addc_u32 s7, s5, 0
	s_ashr_i32 s11, s10, 31
	s_lshr_b32 s11, s11, 26
	s_add_i32 s11, s10, s11
	s_andn2_b32 s11, s11, 63
	s_sub_i32 s12, s10, s11
	s_lshl_b32 s12, s12, 5
	s_ashr_i32 s13, s12, 31
	v_ashrrev_i32_e32 v38, 3, v36
	s_lshl_b64 s[12:13], s[12:13], 2
	s_waitcnt vmcnt(5)
	v_add_u32_e32 v26, s11, v38
	s_add_u32 s12, s6, s12
	v_lshlrev_b32_e32 v2, 4, v36
	s_addc_u32 s13, s7, s13
	v_and_b32_e32 v40, 0x70, v2
	v_mov_b32_e32 v41, 0
	v_ashrrev_i32_e32 v27, 31, v26
	v_lshl_add_u64 v[28:29], s[12:13], 0, v[40:41]
	v_lshlrev_b64 v[2:3], 13, v[26:27]
	v_lshl_add_u64 v[10:11], v[28:29], 0, v[2:3]
	v_add_u32_e32 v2, 8, v26
	v_ashrrev_i32_e32 v3, 31, v2
	v_lshlrev_b64 v[2:3], 13, v[2:3]
	v_lshl_add_u64 v[12:13], v[28:29], 0, v[2:3]
	global_load_dwordx4 v[2:5], v[10:11], off nt
	global_load_dwordx4 v[6:9], v[12:13], off nt
	v_add_u32_e32 v10, 16, v26
	v_ashrrev_i32_e32 v11, 31, v10
	v_lshlrev_b64 v[10:11], 13, v[10:11]
	v_lshl_add_u64 v[18:19], v[28:29], 0, v[10:11]
	v_add_u32_e32 v10, 24, v26
	v_ashrrev_i32_e32 v11, 31, v10
	v_lshlrev_b64 v[10:11], 13, v[10:11]
	v_lshl_add_u64 v[20:21], v[28:29], 0, v[10:11]
	global_load_dwordx4 v[10:13], v[18:19], off nt
	global_load_dwordx4 v[14:17], v[20:21], off nt
	v_add_u32_e32 v18, 32, v26
	v_ashrrev_i32_e32 v19, 31, v18
	v_lshlrev_b64 v[18:19], 13, v[18:19]
	s_waitcnt vmcnt(8)
	v_lshl_add_u64 v[30:31], v[28:29], 0, v[18:19]
	v_add_u32_e32 v18, 40, v26
	v_ashrrev_i32_e32 v19, 31, v18
	v_lshlrev_b64 v[18:19], 13, v[18:19]
	v_lshl_add_u64 v[32:33], v[28:29], 0, v[18:19]
	global_load_dwordx4 v[18:21], v[30:31], off nt
	global_load_dwordx4 v[22:25], v[32:33], off nt
	v_add_u32_e32 v30, 48, v26
	v_ashrrev_i32_e32 v31, 31, v30
	v_add_u32_e32 v26, 56, v26
	v_lshlrev_b64 v[30:31], 13, v[30:31]
	v_ashrrev_i32_e32 v27, 31, v26
	v_lshl_add_u64 v[34:35], v[28:29], 0, v[30:31]
	v_lshlrev_b64 v[26:27], 13, v[26:27]
	v_lshl_add_u64 v[42:43], v[28:29], 0, v[26:27]
	global_load_dwordx4 v[26:29], v[34:35], off nt
	global_load_dwordx4 v[30:33], v[42:43], off nt
	v_lshlrev_b32_e32 v36, 3, v36
	v_and_b32_e32 v36, 56, v36
	v_add_u32_e32 v42, s15, v40
	v_lshl_add_u64 v[34:35], s[6:7], 0, v[40:41]
	v_lshlrev_b32_e32 v40, 1, v36
	s_movk_i32 s6, 0x84
	v_mul_u32_u24_e32 v39, 0x84, v36
	v_lshl_add_u64 v[36:37], s[8:9], 0, v[40:41]
	v_lshlrev_b32_e32 v40, 2, v38
	v_add3_u32 v39, s15, v39, v40
	v_mul_lo_u32 v40, v38, s6
	s_lshl_b32 s12, s14, 5
	s_lshl_b32 s11, s10, 5
	v_add_u32_e32 v40, v42, v40
	s_mov_b32 s13, s12
	v_mov_b32_e32 v41, v38
	s_branch .LBB0_56

; #define LAS __attribute__((address_space(3)))
; #define TR_LOAD(it_) do { const int kb_ = (it_) / nblk, nb_ = (it_) % nblk; _Pragma("unroll") for (int i = 0; i < 8; ++i) r[i] = *(const f32x4*)(W + (size_t)(kb_ * 64 + 8 * i + (lane >> 3)) * ldw + nb_ * 32 + (lane & 7) * 4); } while (0)
; __device__ __forceinline__ void tr_job(const Ctx& c, int& rot, const float* W, int K, int N, int ldw, bf16_t* WT, int ldt, int row_off) {
;     ...
;     int first = c.gw - (rot % c.ngw); if (first < 0) first += c.ngw;
;     int lane = c.lane; asm volatile("" : "+v"(lane));
;     f32x4 r[8];
;     ...
;     if (first < items) TR_LOAD(first);
;     for (int it = first; it < items; it += c.ngw) { const int kb = it / nblk, nb = it % nblk;
; #pragma unroll
;         for (int i = 0; i < 8; ++i) { LAS float* d = scr + (8 * i + (lane >> 3)) * 33 + (lane & 7) * 4; d[0] = r[i][0]; d[1] = r[i][1]; d[2] = r[i][2]; d[3] = r[i][3]; }
;         if (it + c.ngw < items) TR_LOAD(it + c.ngw);
; __device__ __forceinline__ void phase_prologue(KP P, const Ctx& c) {
;     ...
;     for (int m = 0; m < 3; ++m) tr_job(c, rot, P->in[I_RWRKV] + (size_t)m * D * D, D, D, D, (bf16_t*)(ws + WS_RW1), D, m * D);
.LBB0_58:
	s_mul_hi_u32 s6, s22, 0x4800
	s_mul_i32 s6, s6, s21
	s_sub_i32 s6, 0x4800, s6
	s_sub_i32 s7, s6, s21
	s_cmp_ge_u32 s6, s21
	s_cselect_b32 s6, s7, s6
	s_sub_i32 s7, s6, s21
	s_cmp_ge_u32 s6, s21
	s_cselect_b32 s6, s7, s6
	s_sub_i32 s6, s20, s6
	s_ashr_i32 s7, s6, 31
	s_and_b32 s7, s7, s14
	s_add_i32 s6, s7, s6
	v_mov_b32_e32 v36, v1
	s_cmpk_gt_i32 s6, 0x7ff
	s_cbranch_scc1 .LBB0_63
	s_cmpk_eq_i32 s3, 0x100
	s_cbranch_scc1 .LBB0_63
	s_waitcnt lgkmcnt(0)
	s_add_u32 s4, s4, 0x2000000
	s_addc_u32 s5, s5, 0
	s_ashr_i32 s7, s6, 31
	s_lshr_b32 s7, s7, 26
	s_add_i32 s7, s6, s7
	s_andn2_b32 s7, s7, 63
	s_sub_i32 s10, s6, s7
	s_lshl_b32 s10, s10, 5
	s_ashr_i32 s11, s10, 31
	v_ashrrev_i32_e32 v38, 3, v36
	s_lshl_b64 s[10:11], s[10:11], 2
	s_waitcnt vmcnt(5)
	v_add_u32_e32 v26, s7, v38
	s_add_u32 s10, s4, s10
	v_lshlrev_b32_e32 v2, 4, v36
	s_addc_u32 s11, s5, s11
	v_and_b32_e32 v40, 0x70, v2
	v_mov_b32_e32 v41, 0
	v_ashrrev_i32_e32 v27, 31, v26
	v_lshl_add_u64 v[28:29], s[10:11], 0, v[40:41]
	v_lshlrev_b64 v[2:3], 13, v[26:27]
	v_lshl_add_u64 v[10:11], v[28:29], 0, v[2:3]
	v_add_u32_e32 v2, 8, v26
	v_ashrrev_i32_e32 v3, 31, v2
	v_lshlrev_b64 v[2:3], 13, v[2:3]
	v_lshl_add_u64 v[12:13], v[28:29], 0, v[2:3]
	global_load_dwordx4 v[2:5], v[10:11], off nt
	global_load_dwordx4 v[6:9], v[12:13], off nt
	v_add_u32_e32 v10, 16, v26
	v_ashrrev_i32_e32 v11, 31, v10
	v_lshlrev_b64 v[10:11], 13, v[10:11]
	v_lshl_add_u64 v[18:19], v[28:29], 0, v[10:11]
	v_add_u32_e32 v10, 24, v26
	v_ashrrev_i32_e32 v11, 31, v10
	v_lshlrev_b64 v[10:11], 13, v[10:11]
	v_lshl_add_u64 v[20:21], v[28:29], 0, v[10:11]
	global_load_dwordx4 v[10:13], v[18:19], off nt
	global_load_dwordx4 v[14:17], v[20:21], off nt
	v_add_u32_e32 v18, 32, v26
	v_ashrrev_i32_e32 v19, 31, v18
	v_lshlrev_b64 v[18:19], 13, v[18:19]
	s_waitcnt vmcnt(8)
	v_lshl_add_u64 v[30:31], v[28:29], 0, v[18:19]
	v_add_u32_e32 v18, 40, v26
	v_ashrrev_i32_e32 v19, 31, v18
	v_lshlrev_b64 v[18:19], 13, v[18:19]
	v_lshl_add_u64 v[32:33], v[28:29], 0, v[18:19]
	global_load_dwordx4 v[18:21], v[30:31], off nt
	global_load_dwordx4 v[22:25], v[32:33], off nt
	v_add_u32_e32 v30, 48, v26
	v_ashrrev_i32_e32 v31, 31, v30
	v_add_u32_e32 v26, 56, v26
	v_lshlrev_b64 v[30:31], 13, v[30:31]
	v_ashrrev_i32_e32 v27, 31, v26
	v_lshl_add_u64 v[34:35], v[28:29], 0, v[30:31]
	v_lshlrev_b64 v[26:27], 13, v[26:27]
	v_lshl_add_u64 v[42:43], v[28:29], 0, v[26:27]
	global_load_dwordx4 v[26:29], v[34:35], off nt
	global_load_dwordx4 v[30:33], v[42:43], off nt
	v_lshlrev_b32_e32 v36, 3, v36
	v_and_b32_e32 v36, 56, v36
	v_add_u32_e32 v42, s15, v40
	v_lshl_add_u64 v[34:35], s[4:5], 0, v[40:41]
	v_lshlrev_b32_e32 v40, 1, v36
	s_movk_i32 s4, 0x84
	v_mul_u32_u24_e32 v39, 0x84, v36
	v_lshl_add_u64 v[36:37], s[8:9], 0, v[40:41]
	v_lshlrev_b32_e32 v40, 2, v38
	v_add3_u32 v39, s15, v39, v40
	v_mul_lo_u32 v40, v38, s4
	s_lshl_b32 s10, s14, 5
	s_lshl_b32 s7, s6, 5
	v_add_u32_e32 v40, v42, v40
	s_mov_b32 s11, s10
	v_mov_b32_e32 v41, v38
	s_branch .LBB0_61

; #define LAS __attribute__((address_space(3)))
; #define TR_LOAD(it_) do { const int kb_ = (it_) / nblk, nb_ = (it_) % nblk; _Pragma("unroll") for (int i = 0; i < 8; ++i) r[i] = *(const f32x4*)(W + (size_t)(kb_ * 64 + 8 * i + (lane >> 3)) * ldw + nb_ * 32 + (lane & 7) * 4); } while (0)
; __device__ __forceinline__ void tr_job(const Ctx& c, int& rot, const float* W, int K, int N, int ldw, bf16_t* WT, int ldt, int row_off) {
;     ...
; #pragma unroll
;         for (int i = 0; i < 8; ++i) { LAS float* d = scr + (8 * i + (lane >> 3)) * 33 + (lane & 7) * 4; d[0] = r[i][0]; d[1] = r[i][1]; d[2] = r[i][2]; d[3] = r[i][3]; }
;         if (it + c.ngw < items) TR_LOAD(it + c.ngw);
.LBB0_61:
	v_add_u32_e32 v42, 0x420, v40
	s_waitcnt vmcnt(7)
	ds_write2_b32 v40, v2, v3 offset1:1
	ds_write2_b32 v40, v4, v5 offset0:2 offset1:3
	s_waitcnt vmcnt(6)
	ds_write2_b32 v42, v6, v7 offset1:1
	v_add_u32_e32 v42, 0x428, v40
	ds_write2_b32 v42, v8, v9 offset1:1
	v_add_u32_e32 v42, 0x840, v40
	s_waitcnt vmcnt(5)
	ds_write2_b32 v42, v10, v11 offset1:1
	v_add_u32_e32 v42, 0x848, v40
	ds_write2_b32 v42, v12, v13 offset1:1
	v_add_u32_e32 v42, 0xc60, v40
	s_waitcnt vmcnt(4)
	ds_write2_b32 v42, v14, v15 offset1:1
	v_add_u32_e32 v42, 0xc68, v40
	ds_write2_b32 v42, v16, v17 offset1:1
	v_add_u32_e32 v42, 0x1080, v40
	s_waitcnt vmcnt(3)
	ds_write2_b32 v42, v18, v19 offset1:1
	v_add_u32_e32 v42, 0x1088, v40
	ds_write2_b32 v42, v20, v21 offset1:1
	v_add_u32_e32 v42, 0x14a0, v40
	s_waitcnt vmcnt(2)
	ds_write2_b32 v42, v22, v23 offset1:1
	v_add_u32_e32 v42, 0x14a8, v40
	ds_write2_b32 v42, v24, v25 offset1:1
	v_add_u32_e32 v42, 0x18c0, v40
	s_add_i32 s12, s6, s14
	s_waitcnt vmcnt(1)
	ds_write2_b32 v42, v26, v27 offset1:1
	v_add_u32_e32 v42, 0x18c8, v40
	s_cmpk_gt_i32 s12, 0x7ff
	ds_write2_b32 v42, v28, v29 offset1:1
	v_add_u32_e32 v42, 0x1ce0, v40
	s_cselect_b64 s[4:5], -1, 0
	s_waitcnt vmcnt(0)
	ds_write2_b32 v42, v30, v31 offset1:1
	v_add_u32_e32 v42, 0x1ce8, v40
	s_and_b64 vcc, exec, s[4:5]
	ds_write2_b32 v42, v32, v33 offset1:1
	s_cbranch_vccnz .LBB0_60
	s_ashr_i32 s13, s12, 31
	s_lshr_b32 s13, s13, 26
	s_add_i32 s13, s12, s13
	s_and_b32 s23, s13, 0xffffffc0
	s_lshl_b32 s13, s13, 5
	v_add_u32_e32 v26, s23, v38
	s_add_i32 s23, s7, s11
	s_and_b32 s13, s13, 0xfffff800
	s_sub_i32 s24, s23, s13
	s_ashr_i32 s25, s24, 31
	v_ashrrev_i32_e32 v27, 31, v26
	v_lshl_add_u64 v[28:29], s[24:25], 2, v[34:35]
	v_lshlrev_b64 v[2:3], 13, v[26:27]
	v_lshl_add_u64 v[10:11], v[28:29], 0, v[2:3]
	v_add_u32_e32 v2, 8, v26
	v_ashrrev_i32_e32 v3, 31, v2
	v_lshlrev_b64 v[2:3], 13, v[2:3]
	v_lshl_add_u64 v[12:13], v[28:29], 0, v[2:3]
	global_load_dwordx4 v[2:5], v[10:11], off nt
	global_load_dwordx4 v[6:9], v[12:13], off nt
	v_add_u32_e32 v10, 16, v26
	v_ashrrev_i32_e32 v11, 31, v10
	v_lshlrev_b64 v[10:11], 13, v[10:11]
	v_lshl_add_u64 v[18:19], v[28:29], 0, v[10:11]
	v_add_u32_e32 v10, 24, v26
	v_ashrrev_i32_e32 v11, 31, v10
	v_lshlrev_b64 v[10:11], 13, v[10:11]
	v_lshl_add_u64 v[20:21], v[28:29], 0, v[10:11]
	global_load_dwordx4 v[10:13], v[18:19], off nt
	global_load_dwordx4 v[14:17], v[20:21], off nt
	v_add_u32_e32 v18, 32, v26
	v_ashrrev_i32_e32 v19, 31, v18
	v_lshlrev_b64 v[18:19], 13, v[18:19]
	v_lshl_add_u64 v[30:31], v[28:29], 0, v[18:19]
	v_add_u32_e32 v18, 40, v26
	v_ashrrev_i32_e32 v19, 31, v18
	v_lshlrev_b64 v[18:19], 13, v[18:19]
	v_lshl_add_u64 v[32:33], v[28:29], 0, v[18:19]
	global_load_dwordx4 v[18:21], v[30:31], off nt
	global_load_dwordx4 v[22:25], v[32:33], off nt
	v_add_u32_e32 v30, 48, v26
	v_ashrrev_i32_e32 v31, 31, v30
	v_add_u32_e32 v26, 56, v26
	v_lshlrev_b64 v[30:31], 13, v[30:31]
	v_ashrrev_i32_e32 v27, 31, v26
	v_lshl_add_u64 v[42:43], v[28:29], 0, v[30:31]
	v_lshlrev_b64 v[26:27], 13, v[26:27]
	v_lshl_add_u64 v[44:45], v[28:29], 0, v[26:27]
	global_load_dwordx4 v[26:29], v[42:43], off nt
	global_load_dwordx4 v[30:33], v[44:45], off nt
	s_branch .LBB0_60

; #define TR_LOAD(it_) do { const int kb_ = (it_) / nblk, nb_ = (it_) % nblk; _Pragma("unroll") for (int i = 0; i < 8; ++i) r[i] = *(const f32x4*)(W + (size_t)(kb_ * 64 + 8 * i + (lane >> 3)) * ldw + nb_ * 32 + (lane & 7) * 4); } while (0)
; __device__ __forceinline__ void tr_job(const Ctx& c, int& rot, const float* W, int K, int N, int ldw, bf16_t* WT, int ldt, int row_off) {
;     ...
;     int first = c.gw - (rot % c.ngw); if (first < 0) first += c.ngw;
;     int lane = c.lane; asm volatile("" : "+v"(lane));
;     f32x4 r[8];
;     ...
;     if (first < items) TR_LOAD(first);
; __device__ __forceinline__ void phase_prologue(KP P, const Ctx& c) {
;     ...
;     for (int d = 0; d < 2; ++d) {
;         tr_job(c, rot, P->in[I_RWDEC1] + (size_t)d * D * 96, D, 96, 96, (bf16_t*)(ws + WS_RW1), D, 6144 + d * 96);
;         tr_job(c, rot, P->in[I_RWICL1] + (size_t)d * D * 96, D, 96, 96, (bf16_t*)(ws + WS_RW1), D, 6400 + d * 96);
.LBB0_65:
	s_mul_i32 s6, s12, 0x30000
	s_mul_i32 s27, s12, 0x60
	s_mul_hi_u32 s12, s23, s22
	s_mul_i32 s12, s12, s21
	s_sub_i32 s12, s23, s12
	s_sub_i32 s13, s12, s21
	s_cmp_ge_u32 s12, s21
	s_cselect_b32 s12, s13, s12
	s_sub_i32 s13, s12, s21
	s_cmp_ge_u32 s12, s21
	s_cselect_b32 s12, s13, s12
	s_sub_i32 s12, s20, s12
	s_ashr_i32 s13, s12, 31
	s_and_b32 s13, s13, s14
	s_add_i32 s28, s13, s12
	v_mov_b32_e32 v38, v1
	s_cmpk_gt_i32 s28, 0x5f
	s_cbranch_scc1 .LBB0_70
	s_lshl_b64 s[12:13], s[6:7], 2
	s_waitcnt lgkmcnt(0)
	s_add_u32 s12, s4, s12
	s_mul_hi_i32 s29, s28, 0x55555556
	s_addc_u32 s13, s5, s13
	s_lshr_b32 s30, s29, 31
	s_add_i32 s29, s29, s30
	s_mul_i32 s30, s29, 3
	s_sub_i32 s30, s28, s30
	s_lshl_b32 s30, s30, 5
	s_ashr_i32 s31, s30, 31
	s_lshl_b64 s[30:31], s[30:31], 2
	s_add_u32 s30, s12, s30
	s_waitcnt vmcnt(11)
	v_lshlrev_b32_e32 v2, 4, v38
	v_ashrrev_i32_e32 v40, 3, v38
	s_addc_u32 s31, s13, s31
	v_and_b32_e32 v34, 0x70, v2
	s_waitcnt vmcnt(4)
	v_lshl_add_u32 v32, s29, 6, v40
	v_lshl_add_u64 v[26:27], s[30:31], 0, v[34:35]
	v_mad_i64_i32 v[10:11], s[30:31], v32, s24, v[26:27]
	v_add_u32_e32 v2, 8, v32
	v_mad_i64_i32 v[12:13], s[30:31], v2, s24, v[26:27]
	global_load_dwordx4 v[2:5], v[10:11], off nt
	global_load_dwordx4 v[6:9], v[12:13], off nt
	v_add_u32_e32 v10, 16, v32
	v_mad_i64_i32 v[18:19], s[30:31], v10, s24, v[26:27]
	v_add_u32_e32 v10, 24, v32
	v_mad_i64_i32 v[20:21], s[30:31], v10, s24, v[26:27]
	global_load_dwordx4 v[10:13], v[18:19], off nt
	global_load_dwordx4 v[14:17], v[20:21], off nt
	v_add_u32_e32 v18, 32, v32
	v_mad_i64_i32 v[28:29], s[30:31], v18, s24, v[26:27]
	v_add_u32_e32 v18, 40, v32
	v_mad_i64_i32 v[30:31], s[30:31], v18, s24, v[26:27]
	global_load_dwordx4 v[18:21], v[28:29], off nt
	global_load_dwordx4 v[22:25], v[30:31], off nt
	v_add_u32_e32 v28, 48, v32
	v_mad_i64_i32 v[36:37], s[30:31], v28, s24, v[26:27]
	v_add_u32_e32 v28, 56, v32
	v_mad_i64_i32 v[42:43], s[30:31], v28, s24, v[26:27]
	global_load_dwordx4 v[26:29], v[36:37], off nt
	global_load_dwordx4 v[30:33], v[42:43], off nt
	v_add_u32_e32 v42, s15, v34
	v_lshl_add_u64 v[36:37], s[12:13], 0, v[34:35]
	v_lshlrev_b32_e32 v34, 3, v38
	v_and_b32_e32 v34, 56, v34
	v_mul_u32_u24_e32 v41, 0x84, v34
	v_lshlrev_b32_e32 v34, 1, v34
	v_lshl_add_u64 v[38:39], s[8:9], 0, v[34:35]
	v_lshlrev_b32_e32 v34, 2, v40
	v_mul_lo_u32 v43, v40, s25
	v_add3_u32 v34, s15, v41, v34
	s_lshl_b32 s29, s28, 5
	v_add_u32_e32 v41, s27, v40
	v_add_u32_e32 v42, v42, v43
	s_mov_b32 s30, s26
	s_branch .LBB0_68

; #define LAS __attribute__((address_space(3)))
; #define TR_LOAD(it_) do { const int kb_ = (it_) / nblk, nb_ = (it_) % nblk; _Pragma("unroll") for (int i = 0; i < 8; ++i) r[i] = *(const f32x4*)(W + (size_t)(kb_ * 64 + 8 * i + (lane >> 3)) * ldw + nb_ * 32 + (lane & 7) * 4); } while (0)
; __device__ __forceinline__ void tr_job(const Ctx& c, int& rot, const float* W, int K, int N, int ldw, bf16_t* WT, int ldt, int row_off) {
;     ...
; #pragma unroll
;         for (int i = 0; i < 8; ++i) { LAS float* d = scr + (8 * i + (lane >> 3)) * 33 + (lane & 7) * 4; d[0] = r[i][0]; d[1] = r[i][1]; d[2] = r[i][2]; d[3] = r[i][3]; }
;         if (it + c.ngw < items) TR_LOAD(it + c.ngw);
; __device__ __forceinline__ void phase_prologue(KP P, const Ctx& c) {
;     ...
;         tr_job(c, rot, P->in[I_RWICL1] + (size_t)d * D * 96, D, 96, 96, (bf16_t*)(ws + WS_RW1), D, 6400 + d * 96);
.LBB0_68:
	v_add_u32_e32 v43, 0x420, v42
	s_waitcnt vmcnt(7)
	ds_write2_b32 v42, v2, v3 offset1:1
	ds_write2_b32 v42, v4, v5 offset0:2 offset1:3
	s_waitcnt vmcnt(6)
	ds_write2_b32 v43, v6, v7 offset1:1
	v_add_u32_e32 v43, 0x428, v42
	ds_write2_b32 v43, v8, v9 offset1:1
	v_add_u32_e32 v43, 0x840, v42
	s_waitcnt vmcnt(5)
	ds_write2_b32 v43, v10, v11 offset1:1
	v_add_u32_e32 v43, 0x848, v42
	ds_write2_b32 v43, v12, v13 offset1:1
	v_add_u32_e32 v43, 0xc60, v42
	s_waitcnt vmcnt(4)
	ds_write2_b32 v43, v14, v15 offset1:1
	v_add_u32_e32 v43, 0xc68, v42
	ds_write2_b32 v43, v16, v17 offset1:1
	v_add_u32_e32 v43, 0x1080, v42
	s_waitcnt vmcnt(3)
	ds_write2_b32 v43, v18, v19 offset1:1
	v_add_u32_e32 v43, 0x1088, v42
	ds_write2_b32 v43, v20, v21 offset1:1
	v_add_u32_e32 v43, 0x14a0, v42
	s_waitcnt vmcnt(2)
	ds_write2_b32 v43, v22, v23 offset1:1
	v_add_u32_e32 v43, 0x14a8, v42
	ds_write2_b32 v43, v24, v25 offset1:1
	v_add_u32_e32 v43, 0x18c0, v42
	s_add_i32 s31, s28, s14
	s_waitcnt vmcnt(1)
	ds_write2_b32 v43, v26, v27 offset1:1
	v_add_u32_e32 v43, 0x18c8, v42
	s_cmpk_gt_i32 s31, 0x5f
	ds_write2_b32 v43, v28, v29 offset1:1
	v_add_u32_e32 v43, 0x1ce0, v42
	s_cselect_b64 s[12:13], -1, 0
	s_waitcnt vmcnt(0)
	ds_write2_b32 v43, v30, v31 offset1:1
	v_add_u32_e32 v43, 0x1ce8, v42
	s_and_b64 vcc, exec, s[12:13]
	ds_write2_b32 v43, v32, v33 offset1:1
	s_cbranch_vccnz .LBB0_67
	s_mul_hi_i32 s34, s31, 0x55555556
	s_lshr_b32 s35, s34, 31
	s_add_i32 s34, s34, s35
	v_lshl_add_u32 v32, s34, 6, v40
	s_mulk_i32 s34, 0xffa0
	s_add_i32 s35, s29, s30
	s_add_i32 s34, s35, s34
	s_ashr_i32 s35, s34, 31
	v_lshl_add_u64 v[26:27], s[34:35], 2, v[36:37]
	v_mad_i64_i32 v[10:11], s[34:35], v32, s24, v[26:27]
	v_add_u32_e32 v2, 8, v32
	v_mad_i64_i32 v[12:13], s[34:35], v2, s24, v[26:27]
	global_load_dwordx4 v[2:5], v[10:11], off nt
	global_load_dwordx4 v[6:9], v[12:13], off nt
	v_add_u32_e32 v10, 16, v32
	v_mad_i64_i32 v[18:19], s[34:35], v10, s24, v[26:27]
	v_add_u32_e32 v10, 24, v32
	v_mad_i64_i32 v[20:21], s[34:35], v10, s24, v[26:27]
	global_load_dwordx4 v[10:13], v[18:19], off nt
	global_load_dwordx4 v[14:17], v[20:21], off nt
	v_add_u32_e32 v18, 32, v32
	v_mad_i64_i32 v[28:29], s[34:35], v18, s24, v[26:27]
	v_add_u32_e32 v18, 40, v32
	v_mad_i64_i32 v[30:31], s[34:35], v18, s24, v[26:27]
	global_load_dwordx4 v[18:21], v[28:29], off nt
	global_load_dwordx4 v[22:25], v[30:31], off nt
	v_add_u32_e32 v28, 48, v32
	v_mad_i64_i32 v[44:45], s[34:35], v28, s24, v[26:27]
	v_add_u32_e32 v28, 56, v32
	v_mad_i64_i32 v[46:47], s[34:35], v28, s24, v[26:27]
	global_load_dwordx4 v[26:29], v[44:45], off nt
	global_load_dwordx4 v[30:33], v[46:47], off nt
	s_branch .LBB0_67
.LBB0_70:
	s_add_i32 s12, s23, 0x60
	s_mul_hi_u32 s13, s12, s22
	s_mul_i32 s13, s13, s21
	s_sub_i32 s12, s12, s13
	s_sub_i32 s13, s12, s21
	s_cmp_ge_u32 s12, s21
	s_cselect_b32 s12, s13, s12
	s_sub_i32 s13, s12, s21
	s_cmp_ge_u32 s12, s21
	s_cselect_b32 s12, s13, s12
	s_sub_i32 s12, s20, s12
	s_ashr_i32 s13, s12, 31
	s_and_b32 s13, s13, s14
	s_add_i32 s28, s13, s12
	v_mov_b32_e32 v38, v1
	s_cmpk_gt_i32 s28, 0x5f
	s_cbranch_scc1 .LBB0_64
	s_load_dwordx2 s[12:13], s[18:19], 0xd0
	s_lshl_b64 s[30:31], s[6:7], 2
	s_mul_hi_i32 s6, s28, 0x55555556
	s_waitcnt vmcnt(11)
	v_lshlrev_b32_e32 v2, 4, v38
	v_ashrrev_i32_e32 v40, 3, v38
	s_waitcnt lgkmcnt(0)
	s_add_u32 s12, s12, s30
	s_addc_u32 s13, s13, s31
	s_lshr_b32 s29, s6, 31
	s_add_i32 s6, s6, s29
	s_mul_i32 s29, s6, 3
	s_sub_i32 s29, s28, s29
	s_lshl_b32 s30, s29, 5
	s_ashr_i32 s31, s30, 31
	s_lshl_b64 s[30:31], s[30:31], 2
	s_add_u32 s30, s12, s30
	s_addc_u32 s31, s13, s31
	v_and_b32_e32 v34, 0x70, v2
	s_waitcnt vmcnt(4)
	v_lshl_add_u32 v32, s6, 6, v40
	v_lshl_add_u64 v[26:27], s[30:31], 0, v[34:35]
	v_mad_i64_i32 v[10:11], s[30:31], v32, s24, v[26:27]
	v_add_u32_e32 v2, 8, v32
	v_mad_i64_i32 v[12:13], s[30:31], v2, s24, v[26:27]
	global_load_dwordx4 v[2:5], v[10:11], off nt
	global_load_dwordx4 v[6:9], v[12:13], off nt
	v_add_u32_e32 v10, 16, v32
	v_mad_i64_i32 v[18:19], s[30:31], v10, s24, v[26:27]
	v_add_u32_e32 v10, 24, v32
	v_mad_i64_i32 v[20:21], s[30:31], v10, s24, v[26:27]
	global_load_dwordx4 v[10:13], v[18:19], off nt
	global_load_dwordx4 v[14:17], v[20:21], off nt
	v_add_u32_e32 v18, 32, v32
	v_mad_i64_i32 v[28:29], s[30:31], v18, s24, v[26:27]
	v_add_u32_e32 v18, 40, v32
	v_mad_i64_i32 v[30:31], s[30:31], v18, s24, v[26:27]
	global_load_dwordx4 v[18:21], v[28:29], off nt
	global_load_dwordx4 v[22:25], v[30:31], off nt
	v_add_u32_e32 v28, 48, v32
	v_mad_i64_i32 v[36:37], s[30:31], v28, s24, v[26:27]
	v_add_u32_e32 v28, 56, v32
	v_mad_i64_i32 v[42:43], s[30:31], v28, s24, v[26:27]
	global_load_dwordx4 v[26:29], v[36:37], off nt
	global_load_dwordx4 v[30:33], v[42:43], off nt
	v_add_u32_e32 v42, s15, v34
	v_lshl_add_u64 v[36:37], s[12:13], 0, v[34:35]
	v_lshlrev_b32_e32 v34, 3, v38
	v_and_b32_e32 v34, 56, v34
	v_mul_u32_u24_e32 v41, 0x84, v34
	v_lshlrev_b32_e32 v34, 1, v34
	v_lshl_add_u64 v[38:39], s[8:9], 0, v[34:35]
	v_lshlrev_b32_e32 v34, 2, v40
	v_add3_u32 v34, s15, v41, v34
	v_mul_lo_u32 v43, v40, s25
	v_add_u32_e32 v41, s27, v40
	s_lshl_b32 s27, s14, 5
	s_lshl_b32 s6, s28, 5
	v_add_u32_e32 v42, v42, v43
	s_mov_b32 s29, s27
	s_branch .LBB0_73

; #define LAS __attribute__((address_space(3)))
; #define TR_LOAD(it_) do { const int kb_ = (it_) / nblk, nb_ = (it_) % nblk; _Pragma("unroll") for (int i = 0; i < 8; ++i) r[i] = *(const f32x4*)(W + (size_t)(kb_ * 64 + 8 * i + (lane >> 3)) * ldw + nb_ * 32 + (lane & 7) * 4); } while (0)
; __device__ __forceinline__ void tr_job(const Ctx& c, int& rot, const float* W, int K, int N, int ldw, bf16_t* WT, int ldt, int row_off) {
;     ...
; #pragma unroll
;         for (int i = 0; i < 8; ++i) { LAS float* d = scr + (8 * i + (lane >> 3)) * 33 + (lane & 7) * 4; d[0] = r[i][0]; d[1] = r[i][1]; d[2] = r[i][2]; d[3] = r[i][3]; }
;         if (it + c.ngw < items) TR_LOAD(it + c.ngw);
; __device__ __forceinline__ void phase_prologue(KP P, const Ctx& c) {
;     ...
;     tr_job(c, rot, P->in[I_RWG1], D, 256, 256, (bf16_t*)(ws + WS_RW1), D, 6656);
.LBB0_73:
	v_add_u32_e32 v43, 0x420, v42
	s_waitcnt vmcnt(7)
	ds_write2_b32 v42, v2, v3 offset1:1
	ds_write2_b32 v42, v4, v5 offset0:2 offset1:3
	s_waitcnt vmcnt(6)
	ds_write2_b32 v43, v6, v7 offset1:1
	v_add_u32_e32 v43, 0x428, v42
	ds_write2_b32 v43, v8, v9 offset1:1
	v_add_u32_e32 v43, 0x840, v42
	s_waitcnt vmcnt(5)
	ds_write2_b32 v43, v10, v11 offset1:1
	v_add_u32_e32 v43, 0x848, v42
	ds_write2_b32 v43, v12, v13 offset1:1
	v_add_u32_e32 v43, 0xc60, v42
	s_waitcnt vmcnt(4)
	ds_write2_b32 v43, v14, v15 offset1:1
	v_add_u32_e32 v43, 0xc68, v42
	ds_write2_b32 v43, v16, v17 offset1:1
	v_add_u32_e32 v43, 0x1080, v42
	s_waitcnt vmcnt(3)
	ds_write2_b32 v43, v18, v19 offset1:1
	v_add_u32_e32 v43, 0x1088, v42
	ds_write2_b32 v43, v20, v21 offset1:1
	v_add_u32_e32 v43, 0x14a0, v42
	s_waitcnt vmcnt(2)
	ds_write2_b32 v43, v22, v23 offset1:1
	v_add_u32_e32 v43, 0x14a8, v42
	ds_write2_b32 v43, v24, v25 offset1:1
	v_add_u32_e32 v43, 0x18c0, v42
	s_add_i32 s30, s28, s14
	s_waitcnt vmcnt(1)
	ds_write2_b32 v43, v26, v27 offset1:1
	v_add_u32_e32 v43, 0x18c8, v42
	s_cmpk_gt_i32 s30, 0x5f
	ds_write2_b32 v43, v28, v29 offset1:1
	v_add_u32_e32 v43, 0x1ce0, v42
	s_cselect_b64 s[12:13], -1, 0
	s_waitcnt vmcnt(0)
	ds_write2_b32 v43, v30, v31 offset1:1
	v_add_u32_e32 v43, 0x1ce8, v42
	s_and_b64 vcc, exec, s[12:13]
	ds_write2_b32 v43, v32, v33 offset1:1
	s_cbranch_vccnz .LBB0_72
	s_mul_hi_i32 s31, s30, 0x55555556
	s_lshr_b32 s34, s31, 31
	s_add_i32 s31, s31, s34
	v_lshl_add_u32 v32, s31, 6, v40
	s_mulk_i32 s31, 0xffa0
	s_add_i32 s34, s6, s29
	s_add_i32 s34, s34, s31
	s_ashr_i32 s35, s34, 31
	v_lshl_add_u64 v[26:27], s[34:35], 2, v[36:37]
	v_mad_i64_i32 v[10:11], s[34:35], v32, s24, v[26:27]
	v_add_u32_e32 v2, 8, v32
	v_mad_i64_i32 v[12:13], s[34:35], v2, s24, v[26:27]
	global_load_dwordx4 v[2:5], v[10:11], off nt
	global_load_dwordx4 v[6:9], v[12:13], off nt
	v_add_u32_e32 v10, 16, v32
	v_mad_i64_i32 v[18:19], s[34:35], v10, s24, v[26:27]
	v_add_u32_e32 v10, 24, v32
	v_mad_i64_i32 v[20:21], s[34:35], v10, s24, v[26:27]
	global_load_dwordx4 v[10:13], v[18:19], off nt
	global_load_dwordx4 v[14:17], v[20:21], off nt
	v_add_u32_e32 v18, 32, v32
	v_mad_i64_i32 v[28:29], s[34:35], v18, s24, v[26:27]
	v_add_u32_e32 v18, 40, v32
	v_mad_i64_i32 v[30:31], s[34:35], v18, s24, v[26:27]
	global_load_dwordx4 v[18:21], v[28:29], off nt
	global_load_dwordx4 v[22:25], v[30:31], off nt
	v_add_u32_e32 v28, 48, v32
	v_mad_i64_i32 v[44:45], s[34:35], v28, s24, v[26:27]
	v_add_u32_e32 v28, 56, v32
	v_mad_i64_i32 v[46:47], s[34:35], v28, s24, v[26:27]
	global_load_dwordx4 v[26:29], v[44:45], off nt
	global_load_dwordx4 v[30:33], v[46:47], off nt
	s_branch .LBB0_72
.LBB0_75:
	s_waitcnt lgkmcnt(0)
	s_mul_hi_u32 s4, s22, 0x5180
	s_mul_i32 s4, s4, s21
	s_sub_i32 s4, 0x5180, s4
	s_sub_i32 s5, s4, s21
	s_cmp_ge_u32 s4, s21
	s_cselect_b32 s4, s5, s4
	s_sub_i32 s5, s4, s21
	s_cmp_ge_u32 s4, s21
	s_cselect_b32 s4, s5, s4
	s_sub_i32 s4, s20, s4
	s_ashr_i32 s5, s4, 31
	s_and_b32 s5, s5, s14
	s_add_i32 s6, s5, s4
	v_mov_b32_e32 v36, v1
	s_cmpk_gt_i32 s6, 0xff
	s_cbranch_scc1 .LBB0_80
	s_ashr_i32 s7, s6, 31
	s_lshr_b32 s7, s7, 29
	s_add_i32 s7, s6, s7
	s_load_dwordx2 s[4:5], s[18:19], 0xe0
	s_and_b32 s10, s7, 0x7fffff8
	s_sub_i32 s10, s6, s10
	s_lshl_b32 s10, s10, 5
	s_lshl_b32 s7, s7, 3
	s_ashr_i32 s11, s10, 31
	s_andn2_b32 s7, s7, 63
	v_ashrrev_i32_e32 v38, 3, v36
	s_lshl_b64 s[10:11], s[10:11], 2
	s_waitcnt vmcnt(5)
	v_add_u32_e32 v26, s7, v38
	s_waitcnt lgkmcnt(0)
	s_add_u32 s10, s4, s10
	v_lshlrev_b32_e32 v2, 4, v36
	s_addc_u32 s11, s5, s11
	v_and_b32_e32 v40, 0x70, v2
	v_mov_b32_e32 v41, 0
	v_ashrrev_i32_e32 v27, 31, v26
	v_lshl_add_u64 v[28:29], s[10:11], 0, v[40:41]
	v_lshlrev_b64 v[2:3], 10, v[26:27]
	v_lshl_add_u64 v[10:11], v[28:29], 0, v[2:3]
	v_add_u32_e32 v2, 8, v26
	v_ashrrev_i32_e32 v3, 31, v2
	v_lshlrev_b64 v[2:3], 10, v[2:3]
	v_lshl_add_u64 v[12:13], v[28:29], 0, v[2:3]
	global_load_dwordx4 v[2:5], v[10:11], off nt
	global_load_dwordx4 v[6:9], v[12:13], off nt
	v_add_u32_e32 v10, 16, v26
	v_ashrrev_i32_e32 v11, 31, v10
	v_lshlrev_b64 v[10:11], 10, v[10:11]
	v_lshl_add_u64 v[18:19], v[28:29], 0, v[10:11]
	v_add_u32_e32 v10, 24, v26
	v_ashrrev_i32_e32 v11, 31, v10
	v_lshlrev_b64 v[10:11], 10, v[10:11]
	v_lshl_add_u64 v[20:21], v[28:29], 0, v[10:11]
	global_load_dwordx4 v[10:13], v[18:19], off nt
	global_load_dwordx4 v[14:17], v[20:21], off nt
	v_add_u32_e32 v18, 32, v26
	v_ashrrev_i32_e32 v19, 31, v18
	v_lshlrev_b64 v[18:19], 10, v[18:19]
	s_waitcnt vmcnt(8)
	v_lshl_add_u64 v[30:31], v[28:29], 0, v[18:19]
	v_add_u32_e32 v18, 40, v26
	v_ashrrev_i32_e32 v19, 31, v18
	v_lshlrev_b64 v[18:19], 10, v[18:19]
	v_lshl_add_u64 v[32:33], v[28:29], 0, v[18:19]
	global_load_dwordx4 v[18:21], v[30:31], off nt
	global_load_dwordx4 v[22:25], v[32:33], off nt
	v_add_u32_e32 v30, 48, v26
	v_ashrrev_i32_e32 v31, 31, v30
	v_add_u32_e32 v26, 56, v26
	v_lshlrev_b64 v[30:31], 10, v[30:31]
	v_ashrrev_i32_e32 v27, 31, v26
	v_lshl_add_u64 v[34:35], v[28:29], 0, v[30:31]
	v_lshlrev_b64 v[26:27], 10, v[26:27]
	v_lshl_add_u64 v[42:43], v[28:29], 0, v[26:27]
	global_load_dwordx4 v[26:29], v[34:35], off nt
	global_load_dwordx4 v[30:33], v[42:43], off nt
	v_lshlrev_b32_e32 v36, 3, v36
	v_and_b32_e32 v36, 56, v36
	v_add_u32_e32 v42, s15, v40
	v_lshl_add_u64 v[34:35], s[4:5], 0, v[40:41]
	v_lshlrev_b32_e32 v40, 1, v36
	s_movk_i32 s4, 0x84
	v_mul_u32_u24_e32 v39, 0x84, v36
	v_lshl_add_u64 v[36:37], s[8:9], 0, v[40:41]
	v_lshlrev_b32_e32 v40, 2, v38
	v_add3_u32 v39, s15, v39, v40
	v_mul_lo_u32 v40, v38, s4
	s_lshl_b32 s10, s14, 5
	s_lshl_b32 s7, s6, 5
	v_add_u32_e32 v40, v42, v40
	s_mov_b32 s11, s10
	v_mov_b32_e32 v41, v38
	s_branch .LBB0_78

; #define LAS __attribute__((address_space(3)))
; #define TR_LOAD(it_) do { const int kb_ = (it_) / nblk, nb_ = (it_) % nblk; _Pragma("unroll") for (int i = 0; i < 8; ++i) r[i] = *(const f32x4*)(W + (size_t)(kb_ * 64 + 8 * i + (lane >> 3)) * ldw + nb_ * 32 + (lane & 7) * 4); } while (0)
; __device__ __forceinline__ void tr_job(const Ctx& c, int& rot, const float* W, int K, int N, int ldw, bf16_t* WT, int ldt, int row_off) {
;     ...
; #pragma unroll
;         for (int i = 0; i < 8; ++i) { LAS float* d = scr + (8 * i + (lane >> 3)) * 33 + (lane & 7) * 4; d[0] = r[i][0]; d[1] = r[i][1]; d[2] = r[i][2]; d[3] = r[i][3]; }
;         if (it + c.ngw < items) TR_LOAD(it + c.ngw);
; __device__ __forceinline__ void phase_prologue(KP P, const Ctx& c) {
;     ...
;     tr_job(c, rot, P->in[I_RWWO], D, D, D, (bf16_t*)(ws + WS_RWO), D, 0);
.LBB0_78:
	v_add_u32_e32 v42, 0x420, v40
	s_waitcnt vmcnt(7)
	ds_write2_b32 v40, v2, v3 offset1:1
	ds_write2_b32 v40, v4, v5 offset0:2 offset1:3
	s_waitcnt vmcnt(6)
	ds_write2_b32 v42, v6, v7 offset1:1
	v_add_u32_e32 v42, 0x428, v40
	ds_write2_b32 v42, v8, v9 offset1:1
	v_add_u32_e32 v42, 0x840, v40
	s_waitcnt vmcnt(5)
	ds_write2_b32 v42, v10, v11 offset1:1
	v_add_u32_e32 v42, 0x848, v40
	ds_write2_b32 v42, v12, v13 offset1:1
	v_add_u32_e32 v42, 0xc60, v40
	s_waitcnt vmcnt(4)
	ds_write2_b32 v42, v14, v15 offset1:1
	v_add_u32_e32 v42, 0xc68, v40
	ds_write2_b32 v42, v16, v17 offset1:1
	v_add_u32_e32 v42, 0x1080, v40
	s_waitcnt vmcnt(3)
	ds_write2_b32 v42, v18, v19 offset1:1
	v_add_u32_e32 v42, 0x1088, v40
	ds_write2_b32 v42, v20, v21 offset1:1
	v_add_u32_e32 v42, 0x14a0, v40
	s_waitcnt vmcnt(2)
	ds_write2_b32 v42, v22, v23 offset1:1
	v_add_u32_e32 v42, 0x14a8, v40
	ds_write2_b32 v42, v24, v25 offset1:1
	v_add_u32_e32 v42, 0x18c0, v40
	s_add_i32 s12, s6, s14
	s_waitcnt vmcnt(1)
	ds_write2_b32 v42, v26, v27 offset1:1
	v_add_u32_e32 v42, 0x18c8, v40
	s_cmpk_gt_i32 s12, 0xff
	ds_write2_b32 v42, v28, v29 offset1:1
	v_add_u32_e32 v42, 0x1ce0, v40
	s_cselect_b64 s[4:5], -1, 0
	s_waitcnt vmcnt(0)
	ds_write2_b32 v42, v30, v31 offset1:1
	v_add_u32_e32 v42, 0x1ce8, v40
	s_and_b64 vcc, exec, s[4:5]
	ds_write2_b32 v42, v32, v33 offset1:1
	s_cbranch_vccnz .LBB0_77
	s_ashr_i32 s13, s12, 31
	s_lshr_b32 s13, s13, 29
	s_add_i32 s13, s12, s13
	s_ashr_i32 s13, s13, 3
	v_lshl_add_u32 v26, s13, 6, v38
	s_add_i32 s23, s7, s11
	s_lshl_b32 s13, s13, 8
	s_sub_i32 s24, s23, s13
	s_ashr_i32 s25, s24, 31
	v_ashrrev_i32_e32 v27, 31, v26
	v_lshl_add_u64 v[28:29], s[24:25], 2, v[34:35]
	v_lshlrev_b64 v[2:3], 10, v[26:27]
	v_lshl_add_u64 v[10:11], v[28:29], 0, v[2:3]
	v_add_u32_e32 v2, 8, v26
	v_ashrrev_i32_e32 v3, 31, v2
	v_lshlrev_b64 v[2:3], 10, v[2:3]
	v_lshl_add_u64 v[12:13], v[28:29], 0, v[2:3]
	global_load_dwordx4 v[2:5], v[10:11], off nt
	global_load_dwordx4 v[6:9], v[12:13], off nt
	v_add_u32_e32 v10, 16, v26
	v_ashrrev_i32_e32 v11, 31, v10
	v_lshlrev_b64 v[10:11], 10, v[10:11]
	v_lshl_add_u64 v[18:19], v[28:29], 0, v[10:11]
	v_add_u32_e32 v10, 24, v26
	v_ashrrev_i32_e32 v11, 31, v10
	v_lshlrev_b64 v[10:11], 10, v[10:11]
	v_lshl_add_u64 v[20:21], v[28:29], 0, v[10:11]
	global_load_dwordx4 v[10:13], v[18:19], off nt
	global_load_dwordx4 v[14:17], v[20:21], off nt
	v_add_u32_e32 v18, 32, v26
	v_ashrrev_i32_e32 v19, 31, v18
	v_lshlrev_b64 v[18:19], 10, v[18:19]
	v_lshl_add_u64 v[30:31], v[28:29], 0, v[18:19]
	v_add_u32_e32 v18, 40, v26
	v_ashrrev_i32_e32 v19, 31, v18
	v_lshlrev_b64 v[18:19], 10, v[18:19]
	v_lshl_add_u64 v[32:33], v[28:29], 0, v[18:19]
	global_load_dwordx4 v[18:21], v[30:31], off nt
	global_load_dwordx4 v[22:25], v[32:33], off nt
	v_add_u32_e32 v30, 48, v26
	v_ashrrev_i32_e32 v31, 31, v30
	v_add_u32_e32 v26, 56, v26
	v_lshlrev_b64 v[30:31], 10, v[30:31]
	v_ashrrev_i32_e32 v27, 31, v26
	v_lshl_add_u64 v[42:43], v[28:29], 0, v[30:31]
	v_lshlrev_b64 v[26:27], 10, v[26:27]
	v_lshl_add_u64 v[44:45], v[28:29], 0, v[26:27]
	global_load_dwordx4 v[26:29], v[42:43], off nt
	global_load_dwordx4 v[30:33], v[44:45], off nt
	s_branch .LBB0_77
.LBB0_80:
	s_mul_hi_u32 s4, s22, 0x5280
	s_mul_i32 s4, s4, s21
	s_sub_i32 s4, 0x5280, s4
	s_sub_i32 s5, s4, s21
	s_cmp_ge_u32 s4, s21
	s_cselect_b32 s4, s5, s4
	s_sub_i32 s5, s4, s21
	s_cmp_ge_u32 s4, s21
	s_cselect_b32 s4, s5, s4
	s_sub_i32 s4, s20, s4
	s_ashr_i32 s5, s4, 31
	s_and_b32 s5, s5, s14
	s_add_i32 s6, s5, s4
	v_mov_b32_e32 v36, v1
	s_cmpk_gt_i32 s6, 0x7ff
	s_cbranch_scc1 .LBB0_85
	s_ashr_i32 s7, s6, 31
	s_lshr_b32 s7, s7, 26
	s_add_i32 s7, s6, s7
	s_load_dwordx2 s[4:5], s[18:19], 0xa8
	s_andn2_b32 s7, s7, 63
	s_sub_i32 s10, s6, s7
	s_lshl_b32 s10, s10, 5
	s_ashr_i32 s11, s10, 31
	v_ashrrev_i32_e32 v38, 3, v36
	s_lshl_b64 s[10:11], s[10:11], 2
	s_waitcnt vmcnt(5)
	v_add_u32_e32 v26, s7, v38
	s_waitcnt lgkmcnt(0)
	s_add_u32 s10, s4, s10
	v_lshlrev_b32_e32 v2, 4, v36
	s_addc_u32 s11, s5, s11
	v_and_b32_e32 v40, 0x70, v2
	v_mov_b32_e32 v41, 0
	v_ashrrev_i32_e32 v27, 31, v26
	v_lshl_add_u64 v[28:29], s[10:11], 0, v[40:41]
	v_lshlrev_b64 v[2:3], 13, v[26:27]
	v_lshl_add_u64 v[10:11], v[28:29], 0, v[2:3]
	v_add_u32_e32 v2, 8, v26
	v_ashrrev_i32_e32 v3, 31, v2
	v_lshlrev_b64 v[2:3], 13, v[2:3]
	v_lshl_add_u64 v[12:13], v[28:29], 0, v[2:3]
	global_load_dwordx4 v[2:5], v[10:11], off nt
	global_load_dwordx4 v[6:9], v[12:13], off nt
	v_add_u32_e32 v10, 16, v26
	v_ashrrev_i32_e32 v11, 31, v10
	v_lshlrev_b64 v[10:11], 13, v[10:11]
	v_lshl_add_u64 v[18:19], v[28:29], 0, v[10:11]
	v_add_u32_e32 v10, 24, v26
	v_ashrrev_i32_e32 v11, 31, v10
	v_lshlrev_b64 v[10:11], 13, v[10:11]
	v_lshl_add_u64 v[20:21], v[28:29], 0, v[10:11]
	global_load_dwordx4 v[10:13], v[18:19], off nt
	global_load_dwordx4 v[14:17], v[20:21], off nt
	v_add_u32_e32 v18, 32, v26
	v_ashrrev_i32_e32 v19, 31, v18
	v_lshlrev_b64 v[18:19], 13, v[18:19]
	s_waitcnt vmcnt(8)
	v_lshl_add_u64 v[30:31], v[28:29], 0, v[18:19]
	v_add_u32_e32 v18, 40, v26
	v_ashrrev_i32_e32 v19, 31, v18
	v_lshlrev_b64 v[18:19], 13, v[18:19]
	v_lshl_add_u64 v[32:33], v[28:29], 0, v[18:19]
	global_load_dwordx4 v[18:21], v[30:31], off nt
	global_load_dwordx4 v[22:25], v[32:33], off nt
	v_add_u32_e32 v30, 48, v26
	v_ashrrev_i32_e32 v31, 31, v30
	v_add_u32_e32 v26, 56, v26
	v_lshlrev_b64 v[30:31], 13, v[30:31]
	v_ashrrev_i32_e32 v27, 31, v26
	v_lshl_add_u64 v[34:35], v[28:29], 0, v[30:31]
	v_lshlrev_b64 v[26:27], 13, v[26:27]
	v_lshl_add_u64 v[42:43], v[28:29], 0, v[26:27]
	global_load_dwordx4 v[26:29], v[34:35], off nt
	global_load_dwordx4 v[30:33], v[42:43], off nt
	v_lshlrev_b32_e32 v36, 3, v36
	v_and_b32_e32 v36, 56, v36
	v_add_u32_e32 v42, s15, v40
	v_lshl_add_u64 v[34:35], s[4:5], 0, v[40:41]
	v_lshlrev_b32_e32 v40, 1, v36
	s_movk_i32 s7, 0x84
	v_mul_u32_u24_e32 v39, 0x84, v36
	v_lshl_add_u64 v[36:37], s[16:17], 0, v[40:41]
	v_lshlrev_b32_e32 v40, 2, v38
	s_mov_b64 s[4:5], 0xa000000
	v_add3_u32 v39, s15, v39, v40
	v_mul_lo_u32 v40, v38, s7
	s_lshl_b32 s10, s14, 5
	v_lshl_add_u64 v[36:37], v[36:37], 0, s[4:5]
	s_lshl_b32 s7, s6, 5
	v_add_u32_e32 v40, v42, v40
	s_mov_b32 s11, s10
	v_mov_b32_e32 v41, v38
	s_branch .LBB0_83

; #define TR_LOAD(it_) do { const int kb_ = (it_) / nblk, nb_ = (it_) % nblk; _Pragma("unroll") for (int i = 0; i < 8; ++i) r[i] = *(const f32x4*)(W + (size_t)(kb_ * 64 + 8 * i + (lane >> 3)) * ldw + nb_ * 32 + (lane & 7) * 4); } while (0)
; __device__ __forceinline__ void tr_job(const Ctx& c, int& rot, const float* W, int K, int N, int ldw, bf16_t* WT, int ldt, int row_off) {
;     ...
;     int first = c.gw - (rot % c.ngw); if (first < 0) first += c.ngw;
;     int lane = c.lane; asm volatile("" : "+v"(lane));
;     f32x4 r[8];
;     ...
;     if (first < items) TR_LOAD(first);
; __device__ __forceinline__ void phase_prologue(KP P, const Ctx& c) {
;     ...
;     tr_job(c, rot, P->in[I_RETWIN], D, 16384, 16384, (bf16_t*)(ws + WS_RETIN), D, 0);
.Lpro_keep_ret:
	s_mul_hi_u32 s4, s22, 0x5a80
	s_mul_i32 s4, s4, s21
	s_sub_i32 s4, 0x5a80, s4
	s_sub_i32 s5, s4, s21
	s_cmp_ge_u32 s4, s21
	s_cselect_b32 s4, s5, s4
	s_sub_i32 s5, s4, s21
	s_cmp_ge_u32 s4, s21
	s_cselect_b32 s4, s5, s4
	s_sub_i32 s4, s20, s4
	s_ashr_i32 s5, s4, 31
	s_and_b32 s5, s5, s14
	s_add_i32 s24, s5, s4
	v_mov_b32_e32 v36, v1
	s_cmpk_gt_i32 s24, 0x3fff
	s_cbranch_scc1 .LBB0_90
	s_ashr_i32 s6, s24, 31
	s_lshr_b32 s6, s6, 23
	s_add_i32 s6, s24, s6
	s_load_dwordx2 s[4:5], s[18:19], 0x118
	s_ashr_i32 s7, s6, 9
	s_and_b32 s6, s6, 0x7fffe00
	s_sub_i32 s6, s24, s6
	v_ashrrev_i32_e32 v38, 3, v36
	s_lshl_b32 s6, s6, 5
	s_waitcnt vmcnt(11)
	v_lshl_add_u32 v2, s7, 6, v38
	s_ashr_i32 s7, s6, 31
	s_lshl_b64 s[6:7], s[6:7], 2
	s_waitcnt lgkmcnt(0)
	s_add_u32 s6, s4, s6
	v_lshlrev_b32_e32 v3, 4, v36
	s_addc_u32 s7, s5, s7
	v_and_b32_e32 v40, 0x70, v3
	v_mov_b32_e32 v41, 0
	v_ashrrev_i32_e32 v3, 31, v2
	v_lshl_add_u64 v[4:5], s[6:7], 0, v[40:41]
	v_lshlrev_b64 v[2:3], 16, v[2:3]
	s_waitcnt vmcnt(5)
	v_lshl_add_u64 v[26:27], v[4:5], 0, v[2:3]
	s_mov_b32 s6, 0x80000
	v_add_co_u32_e32 v10, vcc, s6, v26
	s_mov_b32 s7, 0x100000
	s_nop 0
	v_addc_co_u32_e32 v11, vcc, 0, v27, vcc
	v_add_co_u32_e32 v18, vcc, s7, v26
	s_mov_b32 s10, 0x180000
	s_nop 0
	v_addc_co_u32_e32 v19, vcc, 0, v27, vcc
	v_add_co_u32_e32 v20, vcc, s10, v26
	s_mov_b32 s11, 0x200000
	s_nop 0
	v_addc_co_u32_e32 v21, vcc, 0, v27, vcc
	v_add_co_u32_e32 v28, vcc, s11, v26
	s_mov_b32 s12, 0x280000
	s_nop 0
	v_addc_co_u32_e32 v29, vcc, 0, v27, vcc
	s_waitcnt vmcnt(4)
	v_add_co_u32_e32 v30, vcc, s12, v26
	s_mov_b32 s13, 0x300000
	s_nop 0
	v_addc_co_u32_e32 v31, vcc, 0, v27, vcc
	v_add_co_u32_e32 v34, vcc, s13, v26
	s_mov_b32 s23, 0x380000
	s_nop 0
	v_addc_co_u32_e32 v35, vcc, 0, v27, vcc
	v_add_co_u32_e32 v42, vcc, s23, v26
	global_load_dwordx4 v[2:5], v[26:27], off nt
	global_load_dwordx4 v[6:9], v[10:11], off nt
	s_nop 0
	global_load_dwordx4 v[10:13], v[18:19], off nt
	global_load_dwordx4 v[14:17], v[20:21], off nt
	s_nop 0
	global_load_dwordx4 v[18:21], v[28:29], off nt
	global_load_dwordx4 v[22:25], v[30:31], off nt
	v_addc_co_u32_e32 v43, vcc, 0, v27, vcc
	global_load_dwordx4 v[26:29], v[34:35], off nt
	global_load_dwordx4 v[30:33], v[42:43], off nt
	v_lshlrev_b32_e32 v36, 3, v36
	v_and_b32_e32 v36, 56, v36
	v_add_u32_e32 v42, s15, v40
	v_lshl_add_u64 v[34:35], s[4:5], 0, v[40:41]
	v_lshlrev_b32_e32 v40, 1, v36
	s_movk_i32 s25, 0x84
	v_mul_u32_u24_e32 v39, 0x84, v36
	v_lshl_add_u64 v[36:37], s[16:17], 0, v[40:41]
	v_lshlrev_b32_e32 v40, 2, v38
	s_mov_b64 s[4:5], 0xa800000
	v_add3_u32 v39, s15, v39, v40
	v_mul_lo_u32 v40, v38, s25
	s_lshl_b32 s26, s14, 5
	v_lshl_add_u64 v[36:37], v[36:37], 0, s[4:5]
	s_lshl_b32 s25, s24, 5
	v_add_u32_e32 v40, v42, v40
	s_mov_b32 s27, s26
	v_mov_b32_e32 v41, v38
	s_branch .LBB0_88

; #define LAS __attribute__((address_space(3)))
; #define TR_LOAD(it_) do { const int kb_ = (it_) / nblk, nb_ = (it_) % nblk; _Pragma("unroll") for (int i = 0; i < 8; ++i) r[i] = *(const f32x4*)(W + (size_t)(kb_ * 64 + 8 * i + (lane >> 3)) * ldw + nb_ * 32 + (lane & 7) * 4); } while (0)
; __device__ __forceinline__ void tr_job(const Ctx& c, int& rot, const float* W, int K, int N, int ldw, bf16_t* WT, int ldt, int row_off) {
;     ...
; #pragma unroll
;         for (int i = 0; i < 8; ++i) { LAS float* d = scr + (8 * i + (lane >> 3)) * 33 + (lane & 7) * 4; d[0] = r[i][0]; d[1] = r[i][1]; d[2] = r[i][2]; d[3] = r[i][3]; }
;         if (it + c.ngw < items) TR_LOAD(it + c.ngw);
; __device__ __forceinline__ void phase_prologue(KP P, const Ctx& c) {
;     ...
;     tr_job(c, rot, P->in[I_RETWOUT], 4096, D, D, (bf16_t*)(ws + WS_RETOUT), 4096, 0);
.LBB0_88:
	v_add_u32_e32 v42, 0x420, v40
	s_waitcnt vmcnt(7)
	ds_write2_b32 v40, v2, v3 offset1:1
	ds_write2_b32 v40, v4, v5 offset0:2 offset1:3
	s_waitcnt vmcnt(6)
	ds_write2_b32 v42, v6, v7 offset1:1
	v_add_u32_e32 v42, 0x428, v40
	ds_write2_b32 v42, v8, v9 offset1:1
	v_add_u32_e32 v42, 0x840, v40
	s_waitcnt vmcnt(5)
	ds_write2_b32 v42, v10, v11 offset1:1
	v_add_u32_e32 v42, 0x848, v40
	ds_write2_b32 v42, v12, v13 offset1:1
	v_add_u32_e32 v42, 0xc60, v40
	s_waitcnt vmcnt(4)
	ds_write2_b32 v42, v14, v15 offset1:1
	v_add_u32_e32 v42, 0xc68, v40
	ds_write2_b32 v42, v16, v17 offset1:1
	v_add_u32_e32 v42, 0x1080, v40
	s_waitcnt vmcnt(3)
	ds_write2_b32 v42, v18, v19 offset1:1
	v_add_u32_e32 v42, 0x1088, v40
	ds_write2_b32 v42, v20, v21 offset1:1
	v_add_u32_e32 v42, 0x14a0, v40
	s_waitcnt vmcnt(2)
	ds_write2_b32 v42, v22, v23 offset1:1
	v_add_u32_e32 v42, 0x14a8, v40
	ds_write2_b32 v42, v24, v25 offset1:1
	v_add_u32_e32 v42, 0x18c0, v40
	s_add_i32 s28, s24, s14
	s_waitcnt vmcnt(1)
	ds_write2_b32 v42, v26, v27 offset1:1
	v_add_u32_e32 v42, 0x18c8, v40
	s_cmpk_gt_i32 s28, 0x3fff
	ds_write2_b32 v42, v28, v29 offset1:1
	v_add_u32_e32 v42, 0x1ce0, v40
	s_cselect_b64 s[4:5], -1, 0
	s_waitcnt vmcnt(0)
	ds_write2_b32 v42, v30, v31 offset1:1
	v_add_u32_e32 v42, 0x1ce8, v40
	s_and_b64 vcc, exec, s[4:5]
	ds_write2_b32 v42, v32, v33 offset1:1
	s_cbranch_vccnz .LBB0_87
	s_ashr_i32 s29, s28, 31
	s_lshr_b32 s29, s29, 23
	s_add_i32 s29, s28, s29
	s_ashr_i32 s29, s29, 9
	v_lshl_add_u32 v2, s29, 6, v38
	s_add_i32 s30, s25, s27
	s_lshl_b32 s29, s29, 14
	s_sub_i32 s30, s30, s29
	s_ashr_i32 s31, s30, 31
	v_ashrrev_i32_e32 v3, 31, v2
	v_lshl_add_u64 v[4:5], s[30:31], 2, v[34:35]
	v_lshlrev_b64 v[2:3], 16, v[2:3]
	v_lshl_add_u64 v[26:27], v[4:5], 0, v[2:3]
	v_add_co_u32_e32 v10, vcc, s6, v26
	s_nop 1
	v_addc_co_u32_e32 v11, vcc, 0, v27, vcc
	v_add_co_u32_e32 v18, vcc, s7, v26
	global_load_dwordx4 v[2:5], v[26:27], off nt
	global_load_dwordx4 v[6:9], v[10:11], off nt
	v_addc_co_u32_e32 v19, vcc, 0, v27, vcc
	v_add_co_u32_e32 v20, vcc, s10, v26
	s_nop 1
	v_addc_co_u32_e32 v21, vcc, 0, v27, vcc
	v_add_co_u32_e32 v28, vcc, s11, v26
	global_load_dwordx4 v[10:13], v[18:19], off nt
	global_load_dwordx4 v[14:17], v[20:21], off nt
	v_addc_co_u32_e32 v29, vcc, 0, v27, vcc
	v_add_co_u32_e32 v30, vcc, s12, v26
	s_nop 1
	v_addc_co_u32_e32 v31, vcc, 0, v27, vcc
	v_add_co_u32_e32 v42, vcc, s13, v26
	global_load_dwordx4 v[18:21], v[28:29], off nt
	global_load_dwordx4 v[22:25], v[30:31], off nt
	v_addc_co_u32_e32 v43, vcc, 0, v27, vcc
	v_add_co_u32_e32 v44, vcc, s23, v26
	s_nop 1
	v_addc_co_u32_e32 v45, vcc, 0, v27, vcc
	global_load_dwordx4 v[26:29], v[42:43], off nt
	global_load_dwordx4 v[30:33], v[44:45], off nt
	s_branch .LBB0_87
.LBB0_90:
	s_mul_hi_u32 s4, s22, 0x9a80
	s_mul_i32 s4, s4, s21
	s_sub_i32 s4, 0x9a80, s4
	s_sub_i32 s5, s4, s21
	s_cmp_ge_u32 s4, s21
	s_cselect_b32 s4, s5, s4
	s_sub_i32 s5, s4, s21
	s_cmp_ge_u32 s4, s21
	s_cselect_b32 s4, s5, s4
	s_sub_i32 s4, s20, s4
	s_ashr_i32 s5, s4, 31
	s_and_b32 s5, s5, s14
	s_add_i32 s6, s5, s4
	s_cmpk_gt_i32 s6, 0xfff
	s_cbranch_scc1 .LBB0_95
	s_ashr_i32 s7, s6, 31
	s_lshr_b32 s7, s7, 26
	s_add_i32 s7, s6, s7
	s_load_dwordx2 s[4:5], s[18:19], 0x120
	s_andn2_b32 s7, s7, 63
	s_sub_i32 s10, s6, s7
	s_lshl_b32 s10, s10, 5
	s_ashr_i32 s11, s10, 31
	v_ashrrev_i32_e32 v38, 3, v1
	s_lshl_b64 s[10:11], s[10:11], 2
	s_waitcnt vmcnt(5)
	v_add_u32_e32 v26, s7, v38
	s_waitcnt lgkmcnt(0)
	s_add_u32 s10, s4, s10
	v_lshlrev_b32_e32 v2, 4, v1
	s_addc_u32 s11, s5, s11
	v_and_b32_e32 v36, 0x70, v2
	v_mov_b32_e32 v37, 0
	v_ashrrev_i32_e32 v27, 31, v26
	v_lshl_add_u64 v[28:29], s[10:11], 0, v[36:37]
	v_lshlrev_b64 v[2:3], 13, v[26:27]
	v_lshl_add_u64 v[10:11], v[28:29], 0, v[2:3]
	v_add_u32_e32 v2, 8, v26
	v_ashrrev_i32_e32 v3, 31, v2
	v_lshlrev_b64 v[2:3], 13, v[2:3]
	v_lshl_add_u64 v[12:13], v[28:29], 0, v[2:3]
	global_load_dwordx4 v[2:5], v[10:11], off nt
	global_load_dwordx4 v[6:9], v[12:13], off nt
	v_add_u32_e32 v10, 16, v26
	v_ashrrev_i32_e32 v11, 31, v10
	v_lshlrev_b64 v[10:11], 13, v[10:11]
	v_lshl_add_u64 v[18:19], v[28:29], 0, v[10:11]
	v_add_u32_e32 v10, 24, v26
	v_ashrrev_i32_e32 v11, 31, v10
	v_lshlrev_b64 v[10:11], 13, v[10:11]
	v_lshl_add_u64 v[20:21], v[28:29], 0, v[10:11]
	global_load_dwordx4 v[10:13], v[18:19], off nt
	global_load_dwordx4 v[14:17], v[20:21], off nt
	v_add_u32_e32 v18, 32, v26
	v_ashrrev_i32_e32 v19, 31, v18
	v_lshlrev_b64 v[18:19], 13, v[18:19]
	s_waitcnt vmcnt(8)
	v_lshl_add_u64 v[30:31], v[28:29], 0, v[18:19]
	v_add_u32_e32 v18, 40, v26
	v_ashrrev_i32_e32 v19, 31, v18
	v_lshlrev_b64 v[18:19], 13, v[18:19]
	v_lshl_add_u64 v[32:33], v[28:29], 0, v[18:19]
	global_load_dwordx4 v[18:21], v[30:31], off nt
	global_load_dwordx4 v[22:25], v[32:33], off nt
	v_add_u32_e32 v30, 48, v26
	v_ashrrev_i32_e32 v31, 31, v30
	v_add_u32_e32 v26, 56, v26
	v_lshlrev_b64 v[30:31], 13, v[30:31]
	v_ashrrev_i32_e32 v27, 31, v26
	v_lshl_add_u64 v[34:35], v[28:29], 0, v[30:31]
	v_lshlrev_b64 v[26:27], 13, v[26:27]
	v_lshl_add_u64 v[40:41], v[28:29], 0, v[26:27]
	global_load_dwordx4 v[26:29], v[34:35], off nt
	global_load_dwordx4 v[30:33], v[40:41], off nt
	v_lshlrev_b32_e32 v1, 3, v1
	v_and_b32_e32 v1, 56, v1
	v_add_u32_e32 v39, s15, v36
	v_lshl_add_u64 v[34:35], s[4:5], 0, v[36:37]
	s_movk_i32 s7, 0x84
	v_mul_u32_u24_e32 v40, 0x84, v1
	v_lshlrev_b32_e32 v36, 1, v1
	v_lshlrev_b32_e32 v1, 2, v38
	v_lshl_add_u64 v[36:37], s[16:17], 0, v[36:37]
	s_mov_b64 s[4:5], 0xe800000
	v_add3_u32 v1, s15, v40, v1
	v_mul_lo_u32 v40, v38, s7
	s_lshl_b32 s10, s14, 5
	v_lshl_add_u64 v[36:37], v[36:37], 0, s[4:5]
	s_lshl_b32 s7, s6, 5
	v_add_u32_e32 v39, v39, v40
	s_mov_b32 s11, s10
	v_mov_b32_e32 v40, v38
	s_branch .LBB0_93

; #define LAS __attribute__((address_space(3)))
; #define TR_LOAD(it_) do { const int kb_ = (it_) / nblk, nb_ = (it_) % nblk; _Pragma("unroll") for (int i = 0; i < 8; ++i) r[i] = *(const f32x4*)(W + (size_t)(kb_ * 64 + 8 * i + (lane >> 3)) * ldw + nb_ * 32 + (lane & 7) * 4); } while (0)
; __device__ __forceinline__ void tr_job(const Ctx& c, int& rot, const float* W, int K, int N, int ldw, bf16_t* WT, int ldt, int row_off) {
;     ...
; #pragma unroll
;         for (int i = 0; i < 8; ++i) { LAS float* d = scr + (8 * i + (lane >> 3)) * 33 + (lane & 7) * 4; d[0] = r[i][0]; d[1] = r[i][1]; d[2] = r[i][2]; d[3] = r[i][3]; }
;         if (it + c.ngw < items) TR_LOAD(it + c.ngw);
.LBB0_93:
	v_add_u32_e32 v41, 0x420, v39
	s_waitcnt vmcnt(7)
	ds_write2_b32 v39, v2, v3 offset1:1
	ds_write2_b32 v39, v4, v5 offset0:2 offset1:3
	s_waitcnt vmcnt(6)
	ds_write2_b32 v41, v6, v7 offset1:1
	v_add_u32_e32 v41, 0x428, v39
	ds_write2_b32 v41, v8, v9 offset1:1
	v_add_u32_e32 v41, 0x840, v39
	s_waitcnt vmcnt(5)
	ds_write2_b32 v41, v10, v11 offset1:1
	v_add_u32_e32 v41, 0x848, v39
	ds_write2_b32 v41, v12, v13 offset1:1
	v_add_u32_e32 v41, 0xc60, v39
	s_waitcnt vmcnt(4)
	ds_write2_b32 v41, v14, v15 offset1:1
	v_add_u32_e32 v41, 0xc68, v39
	ds_write2_b32 v41, v16, v17 offset1:1
	v_add_u32_e32 v41, 0x1080, v39
	s_waitcnt vmcnt(3)
	ds_write2_b32 v41, v18, v19 offset1:1
	v_add_u32_e32 v41, 0x1088, v39
	ds_write2_b32 v41, v20, v21 offset1:1
	v_add_u32_e32 v41, 0x14a0, v39
	s_waitcnt vmcnt(2)
	ds_write2_b32 v41, v22, v23 offset1:1
	v_add_u32_e32 v41, 0x14a8, v39
	ds_write2_b32 v41, v24, v25 offset1:1
	v_add_u32_e32 v41, 0x18c0, v39
	s_add_i32 s12, s6, s14
	s_waitcnt vmcnt(1)
	ds_write2_b32 v41, v26, v27 offset1:1
	v_add_u32_e32 v41, 0x18c8, v39
	s_cmpk_gt_i32 s12, 0xfff
	ds_write2_b32 v41, v28, v29 offset1:1
	v_add_u32_e32 v41, 0x1ce0, v39
	s_cselect_b64 s[4:5], -1, 0
	s_waitcnt vmcnt(0)
	ds_write2_b32 v41, v30, v31 offset1:1
	v_add_u32_e32 v41, 0x1ce8, v39
	s_and_b64 vcc, exec, s[4:5]
	ds_write2_b32 v41, v32, v33 offset1:1
	s_cbranch_vccnz .LBB0_92
	s_ashr_i32 s13, s12, 31
	s_lshr_b32 s13, s13, 26
	s_add_i32 s13, s12, s13
	s_and_b32 s15, s13, 0xffffffc0
	s_lshl_b32 s13, s13, 5
	v_add_u32_e32 v26, s15, v38
	s_add_i32 s15, s7, s11
	s_and_b32 s13, s13, 0xfffff800
	s_sub_i32 s20, s15, s13
	s_ashr_i32 s21, s20, 31
	v_ashrrev_i32_e32 v27, 31, v26
	v_lshl_add_u64 v[28:29], s[20:21], 2, v[34:35]
	v_lshlrev_b64 v[2:3], 13, v[26:27]
	v_lshl_add_u64 v[10:11], v[28:29], 0, v[2:3]
	v_add_u32_e32 v2, 8, v26
	v_ashrrev_i32_e32 v3, 31, v2
	v_lshlrev_b64 v[2:3], 13, v[2:3]
	v_lshl_add_u64 v[12:13], v[28:29], 0, v[2:3]
	global_load_dwordx4 v[2:5], v[10:11], off nt
	global_load_dwordx4 v[6:9], v[12:13], off nt
	v_add_u32_e32 v10, 16, v26
	v_ashrrev_i32_e32 v11, 31, v10
	v_lshlrev_b64 v[10:11], 13, v[10:11]
	v_lshl_add_u64 v[18:19], v[28:29], 0, v[10:11]
	v_add_u32_e32 v10, 24, v26
	v_ashrrev_i32_e32 v11, 31, v10
	v_lshlrev_b64 v[10:11], 13, v[10:11]
	v_lshl_add_u64 v[20:21], v[28:29], 0, v[10:11]
	global_load_dwordx4 v[10:13], v[18:19], off nt
	global_load_dwordx4 v[14:17], v[20:21], off nt
	v_add_u32_e32 v18, 32, v26
	v_ashrrev_i32_e32 v19, 31, v18
	v_lshlrev_b64 v[18:19], 13, v[18:19]
	v_lshl_add_u64 v[30:31], v[28:29], 0, v[18:19]
	v_add_u32_e32 v18, 40, v26
	v_ashrrev_i32_e32 v19, 31, v18
	v_lshlrev_b64 v[18:19], 13, v[18:19]
	v_lshl_add_u64 v[32:33], v[28:29], 0, v[18:19]
	global_load_dwordx4 v[18:21], v[30:31], off nt
	global_load_dwordx4 v[22:25], v[32:33], off nt
	v_add_u32_e32 v30, 48, v26
	v_ashrrev_i32_e32 v31, 31, v30
	v_add_u32_e32 v26, 56, v26
	v_lshlrev_b64 v[30:31], 13, v[30:31]
	v_ashrrev_i32_e32 v27, 31, v26
	v_lshl_add_u64 v[42:43], v[28:29], 0, v[30:31]
	v_lshlrev_b64 v[26:27], 13, v[26:27]
	v_lshl_add_u64 v[44:45], v[28:29], 0, v[26:27]
	global_load_dwordx4 v[26:29], v[42:43], off nt
	global_load_dwordx4 v[30:33], v[44:45], off nt
	s_branch .LBB0_92

; __device__ __forceinline__ void phase_prologue(KP P, const Ctx& c) {
;     ...
;     for (size_t i0 = c.gtid; i0 < (size_t)4 * D * D / 8; i0 += 4 * (size_t)c.ngt) { f32x4 a[4], b[4];
; #pragma unroll
;         for (int u = 0; u < 4; ++u) { const size_t i = i0 + (size_t)u * c.ngt; if (i < (size_t)4 * D * D / 8) { a[u] = *(const f32x4*)(P->in[I_PWQ] + i * 8); b[u] = *(const f32x4*)(P->in[I_PWQ] + i * 8 + 4); } }
; #pragma unroll
;         for (int u = 0; u < 4; ++u) { const size_t i = i0 + (size_t)u * c.ngt; if (i < (size_t)4 * D * D / 8)
;             *(u32x4*)((bf16_t*)(ws + WS_WQN) + i * 8) = (u32x4){cvt_pk_bf16(a[u][0], a[u][1]), cvt_pk_bf16(a[u][2], a[u][3]), cvt_pk_bf16(b[u][0], b[u][1]), cvt_pk_bf16(b[u][2], b[u][3])}; } }
.LBB0_98:
	global_load_dwordx4 v[26:29], v[38:39], off offset:16 nt
	global_load_dwordx4 v[30:33], v[38:39], off nt
	v_lshl_add_u64 v[48:49], v[50:51], 0, s[10:11]
	v_cmp_gt_u64_e32 vcc, s[30:31], v[48:49]
	s_and_saveexec_b64 s[4:5], vcc
	s_cbranch_execz .LBB0_100
	global_load_dwordx4 v[6:9], v[46:47], off nt
	global_load_dwordx4 v[14:17], v[46:47], off offset:-16 nt
.LBB0_100:
	s_or_b64 exec, exec, s[4:5]
	v_lshl_add_u64 v[52:53], s[20:21], 0, v[50:51]
	v_cmp_gt_u64_e64 s[4:5], s[30:31], v[52:53]
	s_and_saveexec_b64 s[6:7], s[4:5]
	s_cbranch_execz .LBB0_102
	s_waitcnt vmcnt(9)
	v_lshl_add_u64 v[18:19], v[38:39], 0, s[14:15]
	global_load_dwordx4 v[10:13], v[18:19], off offset:16 nt
	s_nop 0
	global_load_dwordx4 v[18:21], v[18:19], off nt
.LBB0_102:
	s_or_b64 exec, exec, s[6:7]
	v_lshl_add_u64 v[50:51], s[24:25], 0, v[50:51]
	v_cmp_gt_u64_e64 s[6:7], s[30:31], v[50:51]
	s_and_saveexec_b64 s[40:41], s[6:7]
	s_cbranch_execz .LBB0_104
	s_waitcnt vmcnt(8)
	v_lshl_add_u64 v[22:23], v[38:39], 0, s[26:27]
	global_load_dwordx4 v[2:5], v[22:23], off offset:16 nt
	s_nop 0
	global_load_dwordx4 v[22:25], v[22:23], off nt

; __device__ __forceinline__ void phase_prologue(KP P, const Ctx& c) {
;     ...
;     for (int i = c.gtid; i < 4 * 2048 * 32; i += c.ngt) { const int c8 = i & 31, row = (i >> 5) & 2047, l = i >> 16; const int p = (row >> 7) & 1, col = c8 * 8;
;         u32x4 o = (u32x4){0u, 0u, 0u, 0u};
;         if ((col >> 7) == p) { const float* s = P->in[I_PKEYS] + ((size_t)l * 2048 + row) * 128 + (col & 127); const f32x4 a = *(const f32x4*)s, b = *(const f32x4*)(s + 4);
;             o.x = cvt_pk_bf16(a[0], a[1]); o.y = cvt_pk_bf16(a[2], a[3]); o.z = cvt_pk_bf16(b[0], b[1]); o.w = cvt_pk_bf16(b[2], b[3]); }
;         *(u32x4*)((bf16_t*)(ws + WS_KEYS) + ((size_t)l * 2048 + row) * 256 + col) = o; }
.LBB0_116:
	v_ashrrev_i32_e32 v10, 16, v12
	v_bfe_u32 v2, v12, 12, 1
	v_bfe_u32 v3, v1, 7, 1
	v_cmp_ne_u32_e32 vcc, v3, v2
	v_ashrrev_i32_e32 v11, 31, v10
	s_and_saveexec_b64 s[12:13], vcc
	s_xor_b64 s[12:13], exec, s[12:13]
	v_lshlrev_b64 v[8:9], 20, v[10:11]
	s_or_saveexec_b64 s[12:13], s[12:13]
	v_bfe_u32 v3, v12, 5, 11
	v_mov_b32_e32 v2, 0
	v_lshlrev_b32_e32 v6, 9, v3
	v_mov_b32_e32 v3, 0
	v_mov_b32_e32 v4, 0
	v_mov_b32_e32 v5, 0
	s_xor_b64 exec, exec, s[12:13]
	s_cbranch_execz .LBB0_115
	s_load_dwordx2 s[20:21], s[18:19], 0x48
	v_lshlrev_b64 v[8:9], 20, v[10:11]
	v_and_b32_e32 v2, 0x78, v1
	v_mov_b32_e32 v3, v7
	v_lshlrev_b32_e32 v2, 2, v2
	s_waitcnt lgkmcnt(0)
	v_lshl_add_u64 v[4:5], s[20:21], 0, v[8:9]
	v_lshl_add_u64 v[4:5], v[4:5], 0, v[6:7]
	v_lshl_add_u64 v[10:11], v[4:5], 0, v[2:3]
	global_load_dwordx4 v[2:5], v[10:11], off nt
	global_load_dwordx4 v[14:17], v[10:11], off offset:16 nt
	s_waitcnt vmcnt(1)
	v_cvt_pk_bf16_f32 v2, v2, v3
	v_cvt_pk_bf16_f32 v3, v4, v5
	s_waitcnt vmcnt(0)
	v_cvt_pk_bf16_f32 v4, v14, v15
	v_cvt_pk_bf16_f32 v5, v16, v17
	s_branch .LBB0_115
